# stack: s_setprio 1 before phase barrier + redundant post-barrier lgkmcnt(0) deleted (24 sites) + P10 SwiGLU epilogue rowss loads hoisted
# speedup vs baseline: 1.0104x; 1.0032x over previous
; #define PG8_STAGE(bufoff, gbase, voff) do { _Pragma("unroll") for (int _i = 0; _i < 2; ++_i) \
;         __builtin_amdgcn_global_load_lds((const unsigned*)((const char*)(gbase) + (voff)[_i]), (LAS unsigned*)(lds + (bufoff) + ldsw + _i * 8192), 16, 0, 0); } while (0)
; #define PG8_LDA(dst, b, h) do { _Pragma("unroll") for (int m = 0; m < 4; ++m) _Pragma("unroll") for (int k = 0; k < 2; ++k) dst[m][k] = *(const LAS bf16x8*)(lds + PG8_SA(b, h) + aoff + m * 2048 + k * 1024); } while (0)
; #define PG8_LDB(dst, b, h) do { _Pragma("unroll") for (int n = 0; n < 2; ++n) _Pragma("unroll") for (int k = 0; k < 2; ++k) dst[n][k] = *(const LAS bf16x8*)(lds + PG8_SB(b, h) + boff + n * 2048 + k * 1024); } while (0)
; #define PG8_MMA(ai, bj, At, Bt) do { __builtin_amdgcn_s_setprio(1); _Pragma("unroll") for (int m = 0; m < 4; ++m) _Pragma("unroll") for (int n = 0; n < 2; ++n) _Pragma("unroll") for (int k = 0; k < 2; ++k) \
;         acc[ai][bj][m][n] = __builtin_amdgcn_mfma_f32_16x16x32_bf16(Bt[n][k], At[m][k], acc[ai][bj][m][n], 0, 0, 0); __builtin_amdgcn_s_setprio(0); } while (0)
; #define PG8_WAIT_V(n) asm volatile("s_waitcnt vmcnt(" #n ")" ::: "memory")
; #define PG8_WAIT_L(n) asm volatile("s_waitcnt lgkmcnt(" #n ")" ::: "memory")
; #define PG8_BAR __builtin_amdgcn_s_barrier()
; template <class Epi, class Sched, bool ALIGN_EPI = false, bool SP2 = false>
; __device__ __forceinline__ void gemm_phase(LAS unsigned char* lds, const Gemm g, const Sched& S, const Epi& E) {
;     ...
;             const bool last = (t == nt - 2);
;             const char* a1 = cA + (size_t)(t + 1) * kstep;
;             const char* a2 = last ? nA : cA + (size_t)(t + 2) * kstep; const char* b2 = last ? nB : cB + (size_t)(t + 2) * kstep;
;             const char* a3 = a2 + kstep; const char* b3 = b2 + kstep;
;             if (last && has_next) S.a_ready(nxt);
;             if constexpr (SP2) {
;             PG8_LDB(B0, 0, 0); PG8_LDB(B1, 0, 1); PG8_SCHED; PG8_LDA(At, 0, 0); PG8_STAGE(PG8_SA(1, 1), a1 + hstepA, voffA);
;             PG8_WAIT_V(8); PG8_WAIT_L(0); PG8_BAR; PG8_MMA(0, 0, At, B0); PG8_MMA(0, 1, At, B1); PG8_BAR; PG8_SCHED;
;             PG8_LDA(At, 0, 1); PG8_STAGE(PG8_SB(0, 0), b2, voffB); PG8_STAGE(PG8_SB(0, 1), b2 + hstepB, voffB); PG8_STAGE(PG8_SA(0, 0), a2, voffA);
;             PG8_WAIT_V(8); PG8_WAIT_L(0); PG8_BAR; PG8_MMA(1, 0, At, B0); PG8_MMA(1, 1, At, B1); PG8_BAR; PG8_SCHED;
.LBB0_349:
	ds_read_b128 v[156:159], v149
	ds_read_b128 v[160:163], v149 offset:1024
	ds_read_b128 v[164:167], v149 offset:2048
	ds_read_b128 v[168:171], v149 offset:3072
	ds_read_b128 v[172:175], v150
	ds_read_b128 v[176:179], v150 offset:1024
	ds_read_b128 v[180:183], v150 offset:2048
	ds_read_b128 v[184:187], v150 offset:3072
	s_add_u32 s24, s22, 0xfff80080
	s_addc_u32 s25, s23, -1
	s_cmp_eq_u32 s58, 28
	s_cselect_b32 s27, s15, s25
	s_cselect_b32 s26, s47, s24
	s_cselect_b32 s25, s13, s55
	s_cselect_b32 s24, s50, s51
	v_lshl_add_u64 v[146:147], s[22:23], 0, v[138:139]
	s_add_i32 m0, s21, 0xc000
	ds_read_b128 v[188:191], v151
	ds_read_b128 v[192:195], v151 offset:1024
	ds_read_b128 v[196:199], v151 offset:2048
	ds_read_b128 v[200:203], v151 offset:3072
	ds_read_b128 v[204:207], v151 offset:4096
	ds_read_b128 v[208:211], v151 offset:5120
	ds_read_b128 v[212:215], v151 offset:6144
	ds_read_b128 v[216:219], v151 offset:7168
	global_load_lds_dwordx4 v[146:147], off
	v_lshl_add_u64 v[146:147], s[22:23], 0, v[140:141]
	s_add_i32 m0, s21, 0xe000
	s_nop 0
	global_load_lds_dwordx4 v[146:147], off
	s_waitcnt vmcnt(8)
	s_waitcnt lgkmcnt(0)
	s_setprio 1
	s_barrier
	v_mfma_f32_16x16x32_bf16 v[126:129], v[156:159], v[188:191], v[126:129]
	v_mfma_f32_16x16x32_bf16 v[122:125], v[164:167], v[188:191], v[122:125]
	v_mfma_f32_16x16x32_bf16 v[118:121], v[156:159], v[196:199], v[118:121]
	v_mfma_f32_16x16x32_bf16 v[110:113], v[164:167], v[196:199], v[110:113]
	v_mfma_f32_16x16x32_bf16 v[102:105], v[156:159], v[204:207], v[102:105]
	v_mfma_f32_16x16x32_bf16 v[94:97], v[164:167], v[204:207], v[94:97]
	v_mfma_f32_16x16x32_bf16 v[86:89], v[156:159], v[212:215], v[86:89]
	v_mfma_f32_16x16x32_bf16 v[78:81], v[164:167], v[212:215], v[78:81]
	v_mfma_f32_16x16x32_bf16 v[126:129], v[160:163], v[192:195], v[126:129]
	v_mfma_f32_16x16x32_bf16 v[122:125], v[168:171], v[192:195], v[122:125]
	v_mfma_f32_16x16x32_bf16 v[118:121], v[160:163], v[200:203], v[118:121]
	v_mfma_f32_16x16x32_bf16 v[110:113], v[168:171], v[200:203], v[110:113]
	v_mfma_f32_16x16x32_bf16 v[102:105], v[160:163], v[208:211], v[102:105]
	v_mfma_f32_16x16x32_bf16 v[94:97], v[168:171], v[208:211], v[94:97]
	v_mfma_f32_16x16x32_bf16 v[86:89], v[160:163], v[216:219], v[86:89]
	v_mfma_f32_16x16x32_bf16 v[78:81], v[168:171], v[216:219], v[78:81]
	s_setprio 0
	s_setprio 1
	v_mfma_f32_16x16x32_bf16 v[114:117], v[172:175], v[188:191], v[114:117]
	v_mfma_f32_16x16x32_bf16 v[106:109], v[180:183], v[188:191], v[106:109]
	v_mfma_f32_16x16x32_bf16 v[98:101], v[172:175], v[196:199], v[98:101]
	v_mfma_f32_16x16x32_bf16 v[90:93], v[180:183], v[196:199], v[90:93]
	v_mfma_f32_16x16x32_bf16 v[82:85], v[172:175], v[204:207], v[82:85]
	v_mfma_f32_16x16x32_bf16 v[74:77], v[180:183], v[204:207], v[74:77]
	v_mfma_f32_16x16x32_bf16 v[70:73], v[172:175], v[212:215], v[70:73]
	v_mfma_f32_16x16x32_bf16 v[66:69], v[180:183], v[212:215], v[66:69]
	v_mfma_f32_16x16x32_bf16 v[114:117], v[176:179], v[192:195], v[114:117]
	v_mfma_f32_16x16x32_bf16 v[106:109], v[184:187], v[192:195], v[106:109]
	v_mfma_f32_16x16x32_bf16 v[98:101], v[176:179], v[200:203], v[98:101]
	v_mfma_f32_16x16x32_bf16 v[90:93], v[184:187], v[200:203], v[90:93]
	v_mfma_f32_16x16x32_bf16 v[82:85], v[176:179], v[208:211], v[82:85]
	v_mfma_f32_16x16x32_bf16 v[74:77], v[184:187], v[208:211], v[74:77]
	v_mfma_f32_16x16x32_bf16 v[70:73], v[176:179], v[216:219], v[70:73]
	v_mfma_f32_16x16x32_bf16 v[66:69], v[184:187], v[216:219], v[66:69]
	s_setprio 0
	s_barrier
	s_add_i32 s59, s40, s28
	v_lshl_add_u64 v[146:147], s[24:25], 0, v[134:135]
	s_mov_b32 m0, s59
	ds_read_b128 v[188:191], v151 offset:16384
	ds_read_b128 v[192:195], v151 offset:17408
	ds_read_b128 v[196:199], v151 offset:18432
	ds_read_b128 v[200:203], v151 offset:19456
	ds_read_b128 v[204:207], v151 offset:20480
	ds_read_b128 v[208:211], v151 offset:21504
	ds_read_b128 v[212:215], v151 offset:22528
	ds_read_b128 v[216:219], v151 offset:23552
	global_load_lds_dwordx4 v[146:147], off
	s_add_i32 m0, s59, 0x2000
	s_add_u32 s60, s24, 0x80000
	v_lshl_add_u64 v[220:221], s[24:25], 0, v[130:131]
	s_addc_u32 s61, s25, 0
	s_add_i32 s59, s41, s28
	global_load_lds_dwordx4 v[220:221], off
	v_lshl_add_u64 v[222:223], s[60:61], 0, v[134:135]
	s_mov_b32 m0, s59
	v_lshl_add_u64 v[224:225], s[26:27], 0, v[132:133]
	global_load_lds_dwordx4 v[222:223], off
	v_lshl_add_u64 v[222:223], s[60:61], 0, v[130:131]
	s_add_i32 m0, s59, 0x2000
	s_nop 0
	global_load_lds_dwordx4 v[222:223], off
	v_lshl_add_u64 v[222:223], s[26:27], 0, v[136:137]
	s_mov_b32 m0, s21
	s_nop 0
	global_load_lds_dwordx4 v[222:223], off
	s_mov_b32 m0, s31
	s_nop 0
	global_load_lds_dwordx4 v[224:225], off
	s_waitcnt vmcnt(8)
	s_waitcnt lgkmcnt(0)
	s_setprio 1
	s_barrier
; #define PG8_STAGE(bufoff, gbase, voff) do { _Pragma("unroll") for (int _i = 0; _i < 2; ++_i) \
;         __builtin_amdgcn_global_load_lds((const unsigned*)((const char*)(gbase) + (voff)[_i]), (LAS unsigned*)(lds + (bufoff) + ldsw + _i * 8192), 16, 0, 0); } while (0)
; #define PG8_LDA(dst, b, h) do { _Pragma("unroll") for (int m = 0; m < 4; ++m) _Pragma("unroll") for (int k = 0; k < 2; ++k) dst[m][k] = *(const LAS bf16x8*)(lds + PG8_SA(b, h) + aoff + m * 2048 + k * 1024); } while (0)
; #define PG8_LDB(dst, b, h) do { _Pragma("unroll") for (int n = 0; n < 2; ++n) _Pragma("unroll") for (int k = 0; k < 2; ++k) dst[n][k] = *(const LAS bf16x8*)(lds + PG8_SB(b, h) + boff + n * 2048 + k * 1024); } while (0)
; #define PG8_MMA(ai, bj, At, Bt) do { __builtin_amdgcn_s_setprio(1); _Pragma("unroll") for (int m = 0; m < 4; ++m) _Pragma("unroll") for (int n = 0; n < 2; ++n) _Pragma("unroll") for (int k = 0; k < 2; ++k) \
;         acc[ai][bj][m][n] = __builtin_amdgcn_mfma_f32_16x16x32_bf16(Bt[n][k], At[m][k], acc[ai][bj][m][n], 0, 0, 0); __builtin_amdgcn_s_setprio(0); } while (0)
; #define PG8_WAIT_V(n) asm volatile("s_waitcnt vmcnt(" #n ")" ::: "memory")
; #define PG8_WAIT_L(n) asm volatile("s_waitcnt lgkmcnt(" #n ")" ::: "memory")
; #define PG8_BAR __builtin_amdgcn_s_barrier()
; #define PG8_SCHED __builtin_amdgcn_sched_barrier(0)
; template <class Epi, class Sched, bool ALIGN_EPI = false, bool SP2 = false>
; __device__ __forceinline__ void gemm_phase(LAS unsigned char* lds, const Gemm g, const Sched& S, const Epi& E) {
;     ...
;             PG8_WAIT_V(8); PG8_WAIT_L(0); PG8_BAR; PG8_MMA(1, 0, At, B0); PG8_MMA(1, 1, At, B1); PG8_BAR; PG8_SCHED;
;             PG8_LDB(B0, 1, 0); PG8_LDB(B1, 1, 1); PG8_SCHED; PG8_LDA(At, 1, 0); PG8_STAGE(PG8_SA(0, 1), a2 + hstepA, voffA);
;             PG8_WAIT_V(8); PG8_WAIT_L(0); PG8_BAR; PG8_MMA(0, 0, At, B0); PG8_MMA(0, 1, At, B1); PG8_BAR; PG8_SCHED;
	v_mfma_f32_16x16x32_bf16 v[62:65], v[156:159], v[188:191], v[62:65]
	v_mfma_f32_16x16x32_bf16 v[58:61], v[164:167], v[188:191], v[58:61]
	v_mfma_f32_16x16x32_bf16 v[54:57], v[156:159], v[196:199], v[54:57]
	v_mfma_f32_16x16x32_bf16 v[46:49], v[164:167], v[196:199], v[46:49]
	v_mfma_f32_16x16x32_bf16 v[38:41], v[156:159], v[204:207], v[38:41]
	v_mfma_f32_16x16x32_bf16 v[30:33], v[164:167], v[204:207], v[30:33]
	v_mfma_f32_16x16x32_bf16 v[22:25], v[156:159], v[212:215], v[22:25]
	v_mfma_f32_16x16x32_bf16 v[14:17], v[164:167], v[212:215], v[14:17]
	v_mfma_f32_16x16x32_bf16 v[62:65], v[160:163], v[192:195], v[62:65]
	v_mfma_f32_16x16x32_bf16 v[58:61], v[168:171], v[192:195], v[58:61]
	v_mfma_f32_16x16x32_bf16 v[54:57], v[160:163], v[200:203], v[54:57]
	v_mfma_f32_16x16x32_bf16 v[46:49], v[168:171], v[200:203], v[46:49]
	v_mfma_f32_16x16x32_bf16 v[38:41], v[160:163], v[208:211], v[38:41]
	v_mfma_f32_16x16x32_bf16 v[30:33], v[168:171], v[208:211], v[30:33]
	v_mfma_f32_16x16x32_bf16 v[22:25], v[160:163], v[216:219], v[22:25]
	v_mfma_f32_16x16x32_bf16 v[14:17], v[168:171], v[216:219], v[14:17]
	s_setprio 0
	s_setprio 1
	v_mfma_f32_16x16x32_bf16 v[50:53], v[172:175], v[188:191], v[50:53]
	v_mfma_f32_16x16x32_bf16 v[42:45], v[180:183], v[188:191], v[42:45]
	v_mfma_f32_16x16x32_bf16 v[34:37], v[172:175], v[196:199], v[34:37]
	v_mfma_f32_16x16x32_bf16 v[26:29], v[180:183], v[196:199], v[26:29]
	v_mfma_f32_16x16x32_bf16 v[18:21], v[172:175], v[204:207], v[18:21]
	v_mfma_f32_16x16x32_bf16 v[10:13], v[180:183], v[204:207], v[10:13]
	v_mfma_f32_16x16x32_bf16 v[6:9], v[172:175], v[212:215], v[6:9]
	v_mfma_f32_16x16x32_bf16 v[2:5], v[180:183], v[212:215], v[2:5]
	v_mfma_f32_16x16x32_bf16 v[50:53], v[176:179], v[192:195], v[50:53]
	v_mfma_f32_16x16x32_bf16 v[42:45], v[184:187], v[192:195], v[42:45]
	v_mfma_f32_16x16x32_bf16 v[34:37], v[176:179], v[200:203], v[34:37]
	v_mfma_f32_16x16x32_bf16 v[26:29], v[184:187], v[200:203], v[26:29]
	v_mfma_f32_16x16x32_bf16 v[18:21], v[176:179], v[208:211], v[18:21]
	v_mfma_f32_16x16x32_bf16 v[10:13], v[184:187], v[208:211], v[10:13]
	v_mfma_f32_16x16x32_bf16 v[6:9], v[176:179], v[216:219], v[6:9]
	v_mfma_f32_16x16x32_bf16 v[2:5], v[184:187], v[216:219], v[2:5]
	s_setprio 0
	s_barrier
	ds_read_b128 v[156:159], v153
	ds_read_b128 v[160:163], v153 offset:1024
	ds_read_b128 v[164:167], v153 offset:2048
	ds_read_b128 v[168:171], v153 offset:3072
	ds_read_b128 v[172:175], v154
	ds_read_b128 v[176:179], v154 offset:1024
	ds_read_b128 v[180:183], v154 offset:2048
	ds_read_b128 v[184:187], v154 offset:3072
	s_add_u32 s26, s26, 0x80000
	s_addc_u32 s27, s27, 0
	s_mov_b32 m0, s33
	v_lshl_add_u64 v[226:227], s[26:27], 0, v[136:137]
	ds_read_b128 v[188:191], v151 offset:32768
	ds_read_b128 v[192:195], v151 offset:33792
	ds_read_b128 v[196:199], v151 offset:34816
	ds_read_b128 v[200:203], v151 offset:35840
	ds_read_b128 v[204:207], v151 offset:36864
	ds_read_b128 v[208:211], v151 offset:37888
	ds_read_b128 v[212:215], v151 offset:38912
	ds_read_b128 v[216:219], v151 offset:39936
	global_load_lds_dwordx4 v[226:227], off
	v_lshl_add_u64 v[226:227], s[26:27], 0, v[132:133]
	s_mov_b32 m0, s34
	s_nop 0
	global_load_lds_dwordx4 v[226:227], off
	s_waitcnt vmcnt(8)
	s_waitcnt lgkmcnt(0)
	s_setprio 1
	s_barrier
	v_mfma_f32_16x16x32_bf16 v[126:129], v[156:159], v[188:191], v[126:129]
	v_mfma_f32_16x16x32_bf16 v[122:125], v[164:167], v[188:191], v[122:125]
	v_mfma_f32_16x16x32_bf16 v[118:121], v[156:159], v[196:199], v[118:121]
	v_mfma_f32_16x16x32_bf16 v[110:113], v[164:167], v[196:199], v[110:113]
	v_mfma_f32_16x16x32_bf16 v[102:105], v[156:159], v[204:207], v[102:105]
	v_mfma_f32_16x16x32_bf16 v[94:97], v[164:167], v[204:207], v[94:97]
	v_mfma_f32_16x16x32_bf16 v[86:89], v[156:159], v[212:215], v[86:89]
	v_mfma_f32_16x16x32_bf16 v[78:81], v[164:167], v[212:215], v[78:81]
	v_mfma_f32_16x16x32_bf16 v[126:129], v[160:163], v[192:195], v[126:129]
	v_mfma_f32_16x16x32_bf16 v[122:125], v[168:171], v[192:195], v[122:125]
	v_mfma_f32_16x16x32_bf16 v[118:121], v[160:163], v[200:203], v[118:121]
	v_mfma_f32_16x16x32_bf16 v[110:113], v[168:171], v[200:203], v[110:113]
	v_mfma_f32_16x16x32_bf16 v[102:105], v[160:163], v[208:211], v[102:105]
	v_mfma_f32_16x16x32_bf16 v[94:97], v[168:171], v[208:211], v[94:97]
	v_mfma_f32_16x16x32_bf16 v[86:89], v[160:163], v[216:219], v[86:89]
	v_mfma_f32_16x16x32_bf16 v[78:81], v[168:171], v[216:219], v[78:81]
	s_setprio 0
	s_setprio 1
	v_mfma_f32_16x16x32_bf16 v[114:117], v[172:175], v[188:191], v[114:117]
	v_mfma_f32_16x16x32_bf16 v[106:109], v[180:183], v[188:191], v[106:109]
	v_mfma_f32_16x16x32_bf16 v[98:101], v[172:175], v[196:199], v[98:101]
	v_mfma_f32_16x16x32_bf16 v[90:93], v[180:183], v[196:199], v[90:93]
	v_mfma_f32_16x16x32_bf16 v[82:85], v[172:175], v[204:207], v[82:85]
	v_mfma_f32_16x16x32_bf16 v[74:77], v[180:183], v[204:207], v[74:77]
	v_mfma_f32_16x16x32_bf16 v[70:73], v[172:175], v[212:215], v[70:73]
	v_mfma_f32_16x16x32_bf16 v[66:69], v[180:183], v[212:215], v[66:69]
	v_mfma_f32_16x16x32_bf16 v[114:117], v[176:179], v[192:195], v[114:117]
	v_mfma_f32_16x16x32_bf16 v[106:109], v[184:187], v[192:195], v[106:109]
	v_mfma_f32_16x16x32_bf16 v[98:101], v[176:179], v[200:203], v[98:101]
	v_mfma_f32_16x16x32_bf16 v[90:93], v[184:187], v[200:203], v[90:93]
	v_mfma_f32_16x16x32_bf16 v[82:85], v[176:179], v[208:211], v[82:85]
	v_mfma_f32_16x16x32_bf16 v[74:77], v[184:187], v[208:211], v[74:77]
	v_mfma_f32_16x16x32_bf16 v[70:73], v[176:179], v[216:219], v[70:73]
	v_mfma_f32_16x16x32_bf16 v[66:69], v[184:187], v[216:219], v[66:69]
	s_setprio 0
	s_barrier
; #define PG8_STAGE(bufoff, gbase, voff) do { _Pragma("unroll") for (int _i = 0; _i < 2; ++_i) \
;         __builtin_amdgcn_global_load_lds((const unsigned*)((const char*)(gbase) + (voff)[_i]), (LAS unsigned*)(lds + (bufoff) + ldsw + _i * 8192), 16, 0, 0); } while (0)
; #define PG8_LDA(dst, b, h) do { _Pragma("unroll") for (int m = 0; m < 4; ++m) _Pragma("unroll") for (int k = 0; k < 2; ++k) dst[m][k] = *(const LAS bf16x8*)(lds + PG8_SA(b, h) + aoff + m * 2048 + k * 1024); } while (0)
; #define PG8_MMA(ai, bj, At, Bt) do { __builtin_amdgcn_s_setprio(1); _Pragma("unroll") for (int m = 0; m < 4; ++m) _Pragma("unroll") for (int n = 0; n < 2; ++n) _Pragma("unroll") for (int k = 0; k < 2; ++k) \
;         acc[ai][bj][m][n] = __builtin_amdgcn_mfma_f32_16x16x32_bf16(Bt[n][k], At[m][k], acc[ai][bj][m][n], 0, 0, 0); __builtin_amdgcn_s_setprio(0); } while (0)
; #define PG8_WAIT_V(n) asm volatile("s_waitcnt vmcnt(" #n ")" ::: "memory")
; #define PG8_WAIT_L(n) asm volatile("s_waitcnt lgkmcnt(" #n ")" ::: "memory")
; #define PG8_BAR __builtin_amdgcn_s_barrier()
; #define PG8_SCHED __builtin_amdgcn_sched_barrier(0)
; template <class Epi, class Sched, bool ALIGN_EPI = false, bool SP2 = false>
; __device__ __forceinline__ void gemm_phase(LAS unsigned char* lds, const Gemm g, const Sched& S, const Epi& E) {
;     ...
;         for (int t = 0; t < nt; t += 2) {
;     ...
;             PG8_LDA(At, 1, 1); PG8_STAGE(PG8_SB(1, 0), b3, voffB); PG8_STAGE(PG8_SB(1, 1), b3 + hstepB, voffB); PG8_STAGE(PG8_SA(1, 0), a3, voffA);
;             PG8_WAIT_V(8); PG8_WAIT_L(0); PG8_BAR; PG8_MMA(1, 0, At, B0); PG8_MMA(1, 1, At, B1); PG8_BAR; PG8_SCHED;
	s_add_i32 s26, s44, s28
	v_lshl_add_u64 v[146:147], v[146:147], 0, s[6:7]
	s_mov_b32 m0, s26
	ds_read_b128 v[188:191], v151 offset:49152
	ds_read_b128 v[192:195], v151 offset:50176
	ds_read_b128 v[196:199], v151 offset:51200
	ds_read_b128 v[200:203], v151 offset:52224
	ds_read_b128 v[204:207], v151 offset:53248
	ds_read_b128 v[208:211], v151 offset:54272
	ds_read_b128 v[212:215], v151 offset:55296
	ds_read_b128 v[216:219], v151 offset:56320
	global_load_lds_dwordx4 v[146:147], off
	s_add_i32 m0, s26, 0x2000
	s_add_u32 s24, s24, 0x80080
	v_lshl_add_u64 v[146:147], v[220:221], 0, s[6:7]
	s_addc_u32 s25, s25, 0
	s_add_i32 s26, s45, s28
	global_load_lds_dwordx4 v[146:147], off
	v_lshl_add_u64 v[146:147], s[24:25], 0, v[134:135]
	s_mov_b32 m0, s26
	s_nop 0
	global_load_lds_dwordx4 v[146:147], off
	v_lshl_add_u64 v[146:147], s[24:25], 0, v[130:131]
	s_add_i32 m0, s26, 0x2000
	s_nop 0
	global_load_lds_dwordx4 v[146:147], off
	v_lshl_add_u64 v[146:147], v[222:223], 0, s[6:7]
	s_mov_b32 m0, s36
	s_nop 0
	global_load_lds_dwordx4 v[146:147], off
	v_lshl_add_u64 v[146:147], v[224:225], 0, s[6:7]
	s_mov_b32 m0, s37
	s_nop 0
	global_load_lds_dwordx4 v[146:147], off
	s_waitcnt vmcnt(8)
	s_waitcnt lgkmcnt(0)
	s_setprio 1
	s_barrier
	v_mfma_f32_16x16x32_bf16 v[62:65], v[156:159], v[188:191], v[62:65]
	v_mfma_f32_16x16x32_bf16 v[58:61], v[164:167], v[188:191], v[58:61]
	v_mfma_f32_16x16x32_bf16 v[54:57], v[156:159], v[196:199], v[54:57]
	v_mfma_f32_16x16x32_bf16 v[46:49], v[164:167], v[196:199], v[46:49]
	v_mfma_f32_16x16x32_bf16 v[38:41], v[156:159], v[204:207], v[38:41]
	v_mfma_f32_16x16x32_bf16 v[30:33], v[164:167], v[204:207], v[30:33]
	v_mfma_f32_16x16x32_bf16 v[22:25], v[156:159], v[212:215], v[22:25]
	v_mfma_f32_16x16x32_bf16 v[14:17], v[164:167], v[212:215], v[14:17]
	v_mfma_f32_16x16x32_bf16 v[62:65], v[160:163], v[192:195], v[62:65]
	v_mfma_f32_16x16x32_bf16 v[58:61], v[168:171], v[192:195], v[58:61]
	v_mfma_f32_16x16x32_bf16 v[54:57], v[160:163], v[200:203], v[54:57]
	v_mfma_f32_16x16x32_bf16 v[46:49], v[168:171], v[200:203], v[46:49]
	v_mfma_f32_16x16x32_bf16 v[38:41], v[160:163], v[208:211], v[38:41]
	v_mfma_f32_16x16x32_bf16 v[30:33], v[168:171], v[208:211], v[30:33]
	v_mfma_f32_16x16x32_bf16 v[22:25], v[160:163], v[216:219], v[22:25]
	v_mfma_f32_16x16x32_bf16 v[14:17], v[168:171], v[216:219], v[14:17]
	s_setprio 0
	s_setprio 1
	v_mfma_f32_16x16x32_bf16 v[50:53], v[172:175], v[188:191], v[50:53]
	v_mfma_f32_16x16x32_bf16 v[42:45], v[180:183], v[188:191], v[42:45]
	v_mfma_f32_16x16x32_bf16 v[34:37], v[172:175], v[196:199], v[34:37]
	v_mfma_f32_16x16x32_bf16 v[26:29], v[180:183], v[196:199], v[26:29]
	v_mfma_f32_16x16x32_bf16 v[18:21], v[172:175], v[204:207], v[18:21]
	v_mfma_f32_16x16x32_bf16 v[10:13], v[180:183], v[204:207], v[10:13]
	v_mfma_f32_16x16x32_bf16 v[6:9], v[172:175], v[212:215], v[6:9]
	v_mfma_f32_16x16x32_bf16 v[2:5], v[180:183], v[212:215], v[2:5]
	v_mfma_f32_16x16x32_bf16 v[50:53], v[176:179], v[192:195], v[50:53]
	v_mfma_f32_16x16x32_bf16 v[42:45], v[184:187], v[192:195], v[42:45]
	v_mfma_f32_16x16x32_bf16 v[34:37], v[176:179], v[200:203], v[34:37]
	v_mfma_f32_16x16x32_bf16 v[26:29], v[184:187], v[200:203], v[26:29]
	v_mfma_f32_16x16x32_bf16 v[18:21], v[176:179], v[208:211], v[18:21]
	v_mfma_f32_16x16x32_bf16 v[10:13], v[184:187], v[208:211], v[10:13]
	v_mfma_f32_16x16x32_bf16 v[6:9], v[176:179], v[216:219], v[6:9]
	v_mfma_f32_16x16x32_bf16 v[2:5], v[184:187], v[216:219], v[2:5]
	s_setprio 0
	s_barrier
	s_add_i32 s58, s58, 2
	s_add_u32 s22, s22, 0x100
	s_addc_u32 s23, s23, 0
	s_add_u32 s51, s51, 0x100
	s_addc_u32 s55, s55, 0
	s_cmp_gt_u32 s58, 29
	s_cbranch_scc0 .LBB0_349
	s_and_b64 vcc, exec, s[10:11]
	s_cbranch_vccz .LBB0_352
	s_barrier

; #define PG8_STAGE(bufoff, gbase, voff) do { _Pragma("unroll") for (int _i = 0; _i < 2; ++_i) \
;         __builtin_amdgcn_global_load_lds((const unsigned*)((const char*)(gbase) + (voff)[_i]), (LAS unsigned*)(lds + (bufoff) + ldsw + _i * 8192), 16, 0, 0); } while (0)
; #define PG8_LDA(dst, b, h) do { _Pragma("unroll") for (int m = 0; m < 4; ++m) _Pragma("unroll") for (int k = 0; k < 2; ++k) dst[m][k] = *(const LAS bf16x8*)(lds + PG8_SA(b, h) + aoff + m * 2048 + k * 1024); } while (0)
; #define PG8_LDB(dst, b, h) do { _Pragma("unroll") for (int n = 0; n < 2; ++n) _Pragma("unroll") for (int k = 0; k < 2; ++k) dst[n][k] = *(const LAS bf16x8*)(lds + PG8_SB(b, h) + boff + n * 2048 + k * 1024); } while (0)
; #define PG8_MMA(ai, bj, At, Bt) do { __builtin_amdgcn_s_setprio(1); _Pragma("unroll") for (int m = 0; m < 4; ++m) _Pragma("unroll") for (int n = 0; n < 2; ++n) _Pragma("unroll") for (int k = 0; k < 2; ++k) \
;         acc[ai][bj][m][n] = __builtin_amdgcn_mfma_f32_16x16x32_bf16(Bt[n][k], At[m][k], acc[ai][bj][m][n], 0, 0, 0); __builtin_amdgcn_s_setprio(0); } while (0)
; #define PG8_WAIT_V(n) asm volatile("s_waitcnt vmcnt(" #n ")" ::: "memory")
; #define PG8_WAIT_L(n) asm volatile("s_waitcnt lgkmcnt(" #n ")" ::: "memory")
; template <class Epi, class Sched, bool ALIGN_EPI = false, bool SP2 = false>
; __device__ __forceinline__ void gemm_phase(LAS unsigned char* lds, const Gemm g, const Sched& S, const Epi& E) {
;     ...
;         for (int t = 0; t < nt; t += 2) {
;             const bool last = (t == nt - 2);
;             const char* a1 = cA + (size_t)(t + 1) * kstep;
;             const char* a2 = last ? nA : cA + (size_t)(t + 2) * kstep; const char* b2 = last ? nB : cB + (size_t)(t + 2) * kstep;
;             const char* a3 = a2 + kstep; const char* b3 = b2 + kstep;
;             if (last && has_next) S.a_ready(nxt);
;             if constexpr (SP2) {
;             PG8_LDB(B0, 0, 0); PG8_LDB(B1, 0, 1); PG8_SCHED; PG8_LDA(At, 0, 0); PG8_STAGE(PG8_SA(1, 1), a1 + hstepA, voffA);
;             PG8_WAIT_V(8); PG8_WAIT_L(0); PG8_BAR; PG8_MMA(0, 0, At, B0); PG8_MMA(0, 1, At, B1); PG8_BAR; PG8_SCHED;
;             PG8_LDA(At, 0, 1); PG8_STAGE(PG8_SB(0, 0), b2, voffB); PG8_STAGE(PG8_SB(0, 1), b2 + hstepB, voffB); PG8_STAGE(PG8_SA(0, 0), a2, voffA);
;             PG8_WAIT_V(8); PG8_WAIT_L(0); PG8_BAR; PG8_MMA(1, 0, At, B0); PG8_MMA(1, 1, At, B1); PG8_BAR; PG8_SCHED;
.LBB0_560:
	s_add_u32 s27, s20, s26
	s_addc_u32 s34, s21, 0
	s_add_u32 s30, s27, 0x100
	s_addc_u32 s31, s34, 0
	s_and_b64 s[28:29], s[24:25], exec
	s_cselect_b32 s29, s1, s31
	s_cselect_b32 s28, s0, s30
	s_add_u32 s26, s16, s26
	s_addc_u32 s30, s17, 0
	s_add_u32 s26, s26, 0x100
	s_addc_u32 s30, s30, 0
	s_and_b64 s[24:25], s[24:25], exec
	s_cselect_b32 s31, s19, s30
	s_cselect_b32 s30, s18, s26
	s_add_u32 s36, s27, 0x18080
	ds_read_b128 v[154:157], v147
	ds_read_b128 v[158:161], v147 offset:1024
	ds_read_b128 v[162:165], v147 offset:2048
	ds_read_b128 v[166:169], v147 offset:3072
	ds_read_b128 v[170:173], v148
	ds_read_b128 v[174:177], v148 offset:1024
	ds_read_b128 v[178:181], v148 offset:2048
	ds_read_b128 v[182:185], v148 offset:3072
	s_addc_u32 s37, s34, 0
	s_add_i32 s73, s54, s39
	s_add_i32 m0, s40, 0xc000
	s_add_i32 s76, s40, 0xe000
	s_add_i32 s70, s73, 0x2000
	s_add_u32 s34, s30, 0x18000
	s_addc_u32 s35, s31, 0
	s_add_i32 s72, s55, s39
	s_add_i32 s71, s72, 0x2000
	s_add_u32 s26, s28, 0x18000
	s_addc_u32 s27, s29, 0
	s_add_i32 s67, s57, s39
	s_add_i32 s65, s67, 0x2000
	s_add_u32 s24, s30, 0x18080
	s_addc_u32 s25, s31, 0
	s_add_i32 s66, s58, s39
	s_add_i32 s63, s66, 0x2000
	v_lshl_add_u64 v[218:219], s[36:37], 0, v[130:131]
	ds_read_b128 v[186:189], v149
	ds_read_b128 v[190:193], v149 offset:1024
	ds_read_b128 v[194:197], v149 offset:2048
	ds_read_b128 v[198:201], v149 offset:3072
	ds_read_b128 v[202:205], v149 offset:4096
	ds_read_b128 v[206:209], v149 offset:5120
	ds_read_b128 v[210:213], v149 offset:6144
	ds_read_b128 v[214:217], v149 offset:7168
	global_load_lds_dwordx4 v[218:219], off
	v_lshl_add_u64 v[218:219], s[36:37], 0, v[134:135]
	s_mov_b32 m0, s76
	s_nop 0
	global_load_lds_dwordx4 v[218:219], off
	s_waitcnt vmcnt(8)
	s_waitcnt lgkmcnt(0)
	s_setprio 1
	s_barrier
	v_mfma_f32_16x16x32_bf16 v[126:129], v[154:157], v[186:189], v[126:129]
	v_mfma_f32_16x16x32_bf16 v[122:125], v[162:165], v[186:189], v[122:125]
	v_mfma_f32_16x16x32_bf16 v[118:121], v[154:157], v[194:197], v[118:121]
	v_mfma_f32_16x16x32_bf16 v[110:113], v[162:165], v[194:197], v[110:113]
	v_mfma_f32_16x16x32_bf16 v[102:105], v[154:157], v[202:205], v[102:105]
	v_mfma_f32_16x16x32_bf16 v[94:97], v[162:165], v[202:205], v[94:97]
	v_mfma_f32_16x16x32_bf16 v[86:89], v[154:157], v[210:213], v[86:89]
	v_mfma_f32_16x16x32_bf16 v[78:81], v[162:165], v[210:213], v[78:81]
	v_mfma_f32_16x16x32_bf16 v[126:129], v[158:161], v[190:193], v[126:129]
	v_mfma_f32_16x16x32_bf16 v[122:125], v[166:169], v[190:193], v[122:125]
	v_mfma_f32_16x16x32_bf16 v[118:121], v[158:161], v[198:201], v[118:121]
	v_mfma_f32_16x16x32_bf16 v[110:113], v[166:169], v[198:201], v[110:113]
	v_mfma_f32_16x16x32_bf16 v[102:105], v[158:161], v[206:209], v[102:105]
	v_mfma_f32_16x16x32_bf16 v[94:97], v[166:169], v[206:209], v[94:97]
	v_mfma_f32_16x16x32_bf16 v[86:89], v[158:161], v[214:217], v[86:89]
	v_mfma_f32_16x16x32_bf16 v[78:81], v[166:169], v[214:217], v[78:81]
	s_setprio 0
	s_setprio 1
	v_mfma_f32_16x16x32_bf16 v[114:117], v[170:173], v[186:189], v[114:117]
	v_mfma_f32_16x16x32_bf16 v[106:109], v[178:181], v[186:189], v[106:109]
	v_mfma_f32_16x16x32_bf16 v[98:101], v[170:173], v[194:197], v[98:101]
	v_mfma_f32_16x16x32_bf16 v[90:93], v[178:181], v[194:197], v[90:93]
	v_mfma_f32_16x16x32_bf16 v[82:85], v[170:173], v[202:205], v[82:85]
	v_mfma_f32_16x16x32_bf16 v[74:77], v[178:181], v[202:205], v[74:77]
	v_mfma_f32_16x16x32_bf16 v[70:73], v[170:173], v[210:213], v[70:73]
	v_mfma_f32_16x16x32_bf16 v[66:69], v[178:181], v[210:213], v[66:69]
	v_mfma_f32_16x16x32_bf16 v[114:117], v[174:177], v[190:193], v[114:117]
	v_mfma_f32_16x16x32_bf16 v[106:109], v[182:185], v[190:193], v[106:109]
	v_mfma_f32_16x16x32_bf16 v[98:101], v[174:177], v[198:201], v[98:101]
	v_mfma_f32_16x16x32_bf16 v[90:93], v[182:185], v[198:201], v[90:93]
	v_mfma_f32_16x16x32_bf16 v[82:85], v[174:177], v[206:209], v[82:85]
	v_mfma_f32_16x16x32_bf16 v[74:77], v[182:185], v[206:209], v[74:77]
	v_mfma_f32_16x16x32_bf16 v[70:73], v[174:177], v[214:217], v[70:73]
	v_mfma_f32_16x16x32_bf16 v[66:69], v[182:185], v[214:217], v[66:69]
	s_setprio 0
	s_barrier
	s_mov_b32 m0, s73
	v_lshl_add_u64 v[218:219], s[30:31], 0, v[132:133]
	ds_read_b128 v[186:189], v149 offset:16384
	ds_read_b128 v[190:193], v149 offset:17408
	ds_read_b128 v[194:197], v149 offset:18432
	ds_read_b128 v[198:201], v149 offset:19456
	ds_read_b128 v[202:205], v149 offset:20480
	ds_read_b128 v[206:209], v149 offset:21504
	ds_read_b128 v[210:213], v149 offset:22528
	ds_read_b128 v[214:217], v149 offset:23552
	global_load_lds_dwordx4 v[218:219], off
	v_lshl_add_u64 v[220:221], s[30:31], 0, v[136:137]
	s_mov_b32 m0, s70
	v_lshl_add_u64 v[222:223], s[34:35], 0, v[132:133]
	global_load_lds_dwordx4 v[220:221], off
	s_mov_b32 m0, s72
	v_lshl_add_u64 v[224:225], s[28:29], 0, v[134:135]
	global_load_lds_dwordx4 v[222:223], off
	v_lshl_add_u64 v[222:223], s[34:35], 0, v[136:137]
	s_mov_b32 m0, s71
	s_nop 0
	global_load_lds_dwordx4 v[222:223], off
	v_lshl_add_u64 v[222:223], s[28:29], 0, v[130:131]
	s_mov_b32 m0, s40
	s_nop 0
	global_load_lds_dwordx4 v[222:223], off
	s_mov_b32 m0, s33
	s_nop 0
	global_load_lds_dwordx4 v[224:225], off
	s_waitcnt vmcnt(8)
	s_waitcnt lgkmcnt(0)
	s_setprio 1
	s_barrier
; #define PG8_STAGE(bufoff, gbase, voff) do { _Pragma("unroll") for (int _i = 0; _i < 2; ++_i) \
;         __builtin_amdgcn_global_load_lds((const unsigned*)((const char*)(gbase) + (voff)[_i]), (LAS unsigned*)(lds + (bufoff) + ldsw + _i * 8192), 16, 0, 0); } while (0)
; #define PG8_LDA(dst, b, h) do { _Pragma("unroll") for (int m = 0; m < 4; ++m) _Pragma("unroll") for (int k = 0; k < 2; ++k) dst[m][k] = *(const LAS bf16x8*)(lds + PG8_SA(b, h) + aoff + m * 2048 + k * 1024); } while (0)
; #define PG8_LDB(dst, b, h) do { _Pragma("unroll") for (int n = 0; n < 2; ++n) _Pragma("unroll") for (int k = 0; k < 2; ++k) dst[n][k] = *(const LAS bf16x8*)(lds + PG8_SB(b, h) + boff + n * 2048 + k * 1024); } while (0)
; #define PG8_MMA(ai, bj, At, Bt) do { __builtin_amdgcn_s_setprio(1); _Pragma("unroll") for (int m = 0; m < 4; ++m) _Pragma("unroll") for (int n = 0; n < 2; ++n) _Pragma("unroll") for (int k = 0; k < 2; ++k) \
;         acc[ai][bj][m][n] = __builtin_amdgcn_mfma_f32_16x16x32_bf16(Bt[n][k], At[m][k], acc[ai][bj][m][n], 0, 0, 0); __builtin_amdgcn_s_setprio(0); } while (0)
; #define PG8_WAIT_V(n) asm volatile("s_waitcnt vmcnt(" #n ")" ::: "memory")
; #define PG8_WAIT_L(n) asm volatile("s_waitcnt lgkmcnt(" #n ")" ::: "memory")
; #define PG8_BAR __builtin_amdgcn_s_barrier()
; #define PG8_SCHED __builtin_amdgcn_sched_barrier(0)
; template <class Epi, class Sched, bool ALIGN_EPI = false, bool SP2 = false>
; __device__ __forceinline__ void gemm_phase(LAS unsigned char* lds, const Gemm g, const Sched& S, const Epi& E) {
;     ...
;             PG8_WAIT_V(8); PG8_WAIT_L(0); PG8_BAR; PG8_MMA(1, 0, At, B0); PG8_MMA(1, 1, At, B1); PG8_BAR; PG8_SCHED;
;             PG8_LDB(B0, 1, 0); PG8_LDB(B1, 1, 1); PG8_SCHED; PG8_LDA(At, 1, 0); PG8_STAGE(PG8_SA(0, 1), a2 + hstepA, voffA);
;             PG8_WAIT_V(8); PG8_WAIT_L(0); PG8_BAR; PG8_MMA(0, 0, At, B0); PG8_MMA(0, 1, At, B1); PG8_BAR; PG8_SCHED;
	v_mfma_f32_16x16x32_bf16 v[62:65], v[154:157], v[186:189], v[62:65]
	v_mfma_f32_16x16x32_bf16 v[58:61], v[162:165], v[186:189], v[58:61]
	v_mfma_f32_16x16x32_bf16 v[54:57], v[154:157], v[194:197], v[54:57]
	v_mfma_f32_16x16x32_bf16 v[46:49], v[162:165], v[194:197], v[46:49]
	v_mfma_f32_16x16x32_bf16 v[38:41], v[154:157], v[202:205], v[38:41]
	v_mfma_f32_16x16x32_bf16 v[30:33], v[162:165], v[202:205], v[30:33]
	v_mfma_f32_16x16x32_bf16 v[22:25], v[154:157], v[210:213], v[22:25]
	v_mfma_f32_16x16x32_bf16 v[14:17], v[162:165], v[210:213], v[14:17]
	v_mfma_f32_16x16x32_bf16 v[62:65], v[158:161], v[190:193], v[62:65]
	v_mfma_f32_16x16x32_bf16 v[58:61], v[166:169], v[190:193], v[58:61]
	v_mfma_f32_16x16x32_bf16 v[54:57], v[158:161], v[198:201], v[54:57]
	v_mfma_f32_16x16x32_bf16 v[46:49], v[166:169], v[198:201], v[46:49]
	v_mfma_f32_16x16x32_bf16 v[38:41], v[158:161], v[206:209], v[38:41]
	v_mfma_f32_16x16x32_bf16 v[30:33], v[166:169], v[206:209], v[30:33]
	v_mfma_f32_16x16x32_bf16 v[22:25], v[158:161], v[214:217], v[22:25]
	v_mfma_f32_16x16x32_bf16 v[14:17], v[166:169], v[214:217], v[14:17]
	s_setprio 0
	s_setprio 1
	v_mfma_f32_16x16x32_bf16 v[50:53], v[170:173], v[186:189], v[50:53]
	v_mfma_f32_16x16x32_bf16 v[42:45], v[178:181], v[186:189], v[42:45]
	v_mfma_f32_16x16x32_bf16 v[34:37], v[170:173], v[194:197], v[34:37]
	v_mfma_f32_16x16x32_bf16 v[26:29], v[178:181], v[194:197], v[26:29]
	v_mfma_f32_16x16x32_bf16 v[18:21], v[170:173], v[202:205], v[18:21]
	v_mfma_f32_16x16x32_bf16 v[10:13], v[178:181], v[202:205], v[10:13]
	v_mfma_f32_16x16x32_bf16 v[6:9], v[170:173], v[210:213], v[6:9]
	v_mfma_f32_16x16x32_bf16 v[2:5], v[178:181], v[210:213], v[2:5]
	v_mfma_f32_16x16x32_bf16 v[50:53], v[174:177], v[190:193], v[50:53]
	v_mfma_f32_16x16x32_bf16 v[42:45], v[182:185], v[190:193], v[42:45]
	v_mfma_f32_16x16x32_bf16 v[34:37], v[174:177], v[198:201], v[34:37]
	v_mfma_f32_16x16x32_bf16 v[26:29], v[182:185], v[198:201], v[26:29]
	v_mfma_f32_16x16x32_bf16 v[18:21], v[174:177], v[206:209], v[18:21]
	v_mfma_f32_16x16x32_bf16 v[10:13], v[182:185], v[206:209], v[10:13]
	v_mfma_f32_16x16x32_bf16 v[6:9], v[174:177], v[214:217], v[6:9]
	v_mfma_f32_16x16x32_bf16 v[2:5], v[182:185], v[214:217], v[2:5]
	s_setprio 0
	s_barrier
	ds_read_b128 v[154:157], v150
	ds_read_b128 v[158:161], v150 offset:1024
	ds_read_b128 v[162:165], v150 offset:2048
	ds_read_b128 v[166:169], v150 offset:3072
	ds_read_b128 v[170:173], v151
	ds_read_b128 v[174:177], v151 offset:1024
	ds_read_b128 v[178:181], v151 offset:2048
	ds_read_b128 v[182:185], v151 offset:3072
	s_mov_b32 m0, s41
	v_lshl_add_u64 v[226:227], s[26:27], 0, v[130:131]
	ds_read_b128 v[186:189], v149 offset:32768
	ds_read_b128 v[190:193], v149 offset:33792
	ds_read_b128 v[194:197], v149 offset:34816
	ds_read_b128 v[198:201], v149 offset:35840
	ds_read_b128 v[202:205], v149 offset:36864
	ds_read_b128 v[206:209], v149 offset:37888
	ds_read_b128 v[210:213], v149 offset:38912
	ds_read_b128 v[214:217], v149 offset:39936
	global_load_lds_dwordx4 v[226:227], off
	v_lshl_add_u64 v[226:227], s[26:27], 0, v[134:135]
	s_mov_b32 m0, s44
	s_nop 0
	global_load_lds_dwordx4 v[226:227], off
	s_waitcnt vmcnt(8)
	s_waitcnt lgkmcnt(0)
	s_setprio 1
	s_barrier
	v_mfma_f32_16x16x32_bf16 v[126:129], v[154:157], v[186:189], v[126:129]
	v_mfma_f32_16x16x32_bf16 v[122:125], v[162:165], v[186:189], v[122:125]
	v_mfma_f32_16x16x32_bf16 v[118:121], v[154:157], v[194:197], v[118:121]
	v_mfma_f32_16x16x32_bf16 v[110:113], v[162:165], v[194:197], v[110:113]
	v_mfma_f32_16x16x32_bf16 v[102:105], v[154:157], v[202:205], v[102:105]
	v_mfma_f32_16x16x32_bf16 v[94:97], v[162:165], v[202:205], v[94:97]
	v_mfma_f32_16x16x32_bf16 v[86:89], v[154:157], v[210:213], v[86:89]
	v_mfma_f32_16x16x32_bf16 v[78:81], v[162:165], v[210:213], v[78:81]
	v_mfma_f32_16x16x32_bf16 v[126:129], v[158:161], v[190:193], v[126:129]
	v_mfma_f32_16x16x32_bf16 v[122:125], v[166:169], v[190:193], v[122:125]
	v_mfma_f32_16x16x32_bf16 v[118:121], v[158:161], v[198:201], v[118:121]
	v_mfma_f32_16x16x32_bf16 v[110:113], v[166:169], v[198:201], v[110:113]
	v_mfma_f32_16x16x32_bf16 v[102:105], v[158:161], v[206:209], v[102:105]
	v_mfma_f32_16x16x32_bf16 v[94:97], v[166:169], v[206:209], v[94:97]
	v_mfma_f32_16x16x32_bf16 v[86:89], v[158:161], v[214:217], v[86:89]
	v_mfma_f32_16x16x32_bf16 v[78:81], v[166:169], v[214:217], v[78:81]
	s_setprio 0
	s_setprio 1
	v_mfma_f32_16x16x32_bf16 v[114:117], v[170:173], v[186:189], v[114:117]
	v_mfma_f32_16x16x32_bf16 v[106:109], v[178:181], v[186:189], v[106:109]
	v_mfma_f32_16x16x32_bf16 v[98:101], v[170:173], v[194:197], v[98:101]
	v_mfma_f32_16x16x32_bf16 v[90:93], v[178:181], v[194:197], v[90:93]
	v_mfma_f32_16x16x32_bf16 v[82:85], v[170:173], v[202:205], v[82:85]
	v_mfma_f32_16x16x32_bf16 v[74:77], v[178:181], v[202:205], v[74:77]
	v_mfma_f32_16x16x32_bf16 v[70:73], v[170:173], v[210:213], v[70:73]
	v_mfma_f32_16x16x32_bf16 v[66:69], v[178:181], v[210:213], v[66:69]
	v_mfma_f32_16x16x32_bf16 v[114:117], v[174:177], v[190:193], v[114:117]
	v_mfma_f32_16x16x32_bf16 v[106:109], v[182:185], v[190:193], v[106:109]
	v_mfma_f32_16x16x32_bf16 v[98:101], v[174:177], v[198:201], v[98:101]
	v_mfma_f32_16x16x32_bf16 v[90:93], v[182:185], v[198:201], v[90:93]
	v_mfma_f32_16x16x32_bf16 v[82:85], v[174:177], v[206:209], v[82:85]
	v_mfma_f32_16x16x32_bf16 v[74:77], v[182:185], v[206:209], v[74:77]
	v_mfma_f32_16x16x32_bf16 v[70:73], v[174:177], v[214:217], v[70:73]
	v_mfma_f32_16x16x32_bf16 v[66:69], v[182:185], v[214:217], v[66:69]
	s_setprio 0
	s_barrier
; #define PG8_STAGE(bufoff, gbase, voff) do { _Pragma("unroll") for (int _i = 0; _i < 2; ++_i) \
;         __builtin_amdgcn_global_load_lds((const unsigned*)((const char*)(gbase) + (voff)[_i]), (LAS unsigned*)(lds + (bufoff) + ldsw + _i * 8192), 16, 0, 0); } while (0)
; #define PG8_LDA(dst, b, h) do { _Pragma("unroll") for (int m = 0; m < 4; ++m) _Pragma("unroll") for (int k = 0; k < 2; ++k) dst[m][k] = *(const LAS bf16x8*)(lds + PG8_SA(b, h) + aoff + m * 2048 + k * 1024); } while (0)
; #define PG8_MMA(ai, bj, At, Bt) do { __builtin_amdgcn_s_setprio(1); _Pragma("unroll") for (int m = 0; m < 4; ++m) _Pragma("unroll") for (int n = 0; n < 2; ++n) _Pragma("unroll") for (int k = 0; k < 2; ++k) \
;         acc[ai][bj][m][n] = __builtin_amdgcn_mfma_f32_16x16x32_bf16(Bt[n][k], At[m][k], acc[ai][bj][m][n], 0, 0, 0); __builtin_amdgcn_s_setprio(0); } while (0)
; #define PG8_WAIT_V(n) asm volatile("s_waitcnt vmcnt(" #n ")" ::: "memory")
; #define PG8_WAIT_L(n) asm volatile("s_waitcnt lgkmcnt(" #n ")" ::: "memory")
; #define PG8_BAR __builtin_amdgcn_s_barrier()
; #define PG8_SCHED __builtin_amdgcn_sched_barrier(0)
; template <class Epi, class Sched, bool ALIGN_EPI = false, bool SP2 = false>
; __device__ __forceinline__ void gemm_phase(LAS unsigned char* lds, const Gemm g, const Sched& S, const Epi& E) {
;     ...
;         for (int t = 0; t < nt; t += 2) {
;     ...
;             PG8_LDA(At, 1, 1); PG8_STAGE(PG8_SB(1, 0), b3, voffB); PG8_STAGE(PG8_SB(1, 1), b3 + hstepB, voffB); PG8_STAGE(PG8_SA(1, 0), a3, voffA);
;             PG8_WAIT_V(8); PG8_WAIT_L(0); PG8_BAR; PG8_MMA(1, 0, At, B0); PG8_MMA(1, 1, At, B1); PG8_BAR; PG8_SCHED;
	s_mov_b32 m0, s67
	v_lshl_add_u64 v[218:219], v[218:219], 0, s[12:13]
	ds_read_b128 v[186:189], v149 offset:49152
	ds_read_b128 v[190:193], v149 offset:50176
	ds_read_b128 v[194:197], v149 offset:51200
	ds_read_b128 v[198:201], v149 offset:52224
	ds_read_b128 v[202:205], v149 offset:53248
	ds_read_b128 v[206:209], v149 offset:54272
	ds_read_b128 v[210:213], v149 offset:55296
	ds_read_b128 v[214:217], v149 offset:56320
	global_load_lds_dwordx4 v[218:219], off
	v_lshl_add_u64 v[218:219], v[220:221], 0, s[12:13]
	s_mov_b32 m0, s65
	s_nop 0
	global_load_lds_dwordx4 v[218:219], off
	v_lshl_add_u64 v[218:219], s[24:25], 0, v[132:133]
	s_mov_b32 m0, s66
	s_nop 0
	global_load_lds_dwordx4 v[218:219], off
	v_lshl_add_u64 v[218:219], s[24:25], 0, v[136:137]
	s_mov_b32 m0, s63
	s_nop 0
	global_load_lds_dwordx4 v[218:219], off
	v_lshl_add_u64 v[218:219], v[222:223], 0, s[12:13]
	s_mov_b32 m0, s45
	s_nop 0
	global_load_lds_dwordx4 v[218:219], off
	v_lshl_add_u64 v[218:219], v[224:225], 0, s[12:13]
	s_mov_b32 m0, s46
	s_nop 0
	global_load_lds_dwordx4 v[218:219], off
	s_waitcnt vmcnt(8)
	s_waitcnt lgkmcnt(0)
	s_setprio 1
	s_barrier
	v_mfma_f32_16x16x32_bf16 v[62:65], v[154:157], v[186:189], v[62:65]
	v_mfma_f32_16x16x32_bf16 v[58:61], v[162:165], v[186:189], v[58:61]
	v_mfma_f32_16x16x32_bf16 v[54:57], v[154:157], v[194:197], v[54:57]
	v_mfma_f32_16x16x32_bf16 v[46:49], v[162:165], v[194:197], v[46:49]
	v_mfma_f32_16x16x32_bf16 v[38:41], v[154:157], v[202:205], v[38:41]
	v_mfma_f32_16x16x32_bf16 v[30:33], v[162:165], v[202:205], v[30:33]
	v_mfma_f32_16x16x32_bf16 v[22:25], v[154:157], v[210:213], v[22:25]
	v_mfma_f32_16x16x32_bf16 v[14:17], v[162:165], v[210:213], v[14:17]
	v_mfma_f32_16x16x32_bf16 v[62:65], v[158:161], v[190:193], v[62:65]
	v_mfma_f32_16x16x32_bf16 v[58:61], v[166:169], v[190:193], v[58:61]
	v_mfma_f32_16x16x32_bf16 v[54:57], v[158:161], v[198:201], v[54:57]
	v_mfma_f32_16x16x32_bf16 v[46:49], v[166:169], v[198:201], v[46:49]
	v_mfma_f32_16x16x32_bf16 v[38:41], v[158:161], v[206:209], v[38:41]
	v_mfma_f32_16x16x32_bf16 v[30:33], v[166:169], v[206:209], v[30:33]
	v_mfma_f32_16x16x32_bf16 v[22:25], v[158:161], v[214:217], v[22:25]
	v_mfma_f32_16x16x32_bf16 v[14:17], v[166:169], v[214:217], v[14:17]
	s_setprio 0
	s_setprio 1
	v_mfma_f32_16x16x32_bf16 v[50:53], v[170:173], v[186:189], v[50:53]
	v_mfma_f32_16x16x32_bf16 v[42:45], v[178:181], v[186:189], v[42:45]
	v_mfma_f32_16x16x32_bf16 v[34:37], v[170:173], v[194:197], v[34:37]
	v_mfma_f32_16x16x32_bf16 v[26:29], v[178:181], v[194:197], v[26:29]
	v_mfma_f32_16x16x32_bf16 v[18:21], v[170:173], v[202:205], v[18:21]
	v_mfma_f32_16x16x32_bf16 v[10:13], v[178:181], v[202:205], v[10:13]
	v_mfma_f32_16x16x32_bf16 v[6:9], v[170:173], v[210:213], v[6:9]
	v_mfma_f32_16x16x32_bf16 v[2:5], v[178:181], v[210:213], v[2:5]
	v_mfma_f32_16x16x32_bf16 v[50:53], v[174:177], v[190:193], v[50:53]
	v_mfma_f32_16x16x32_bf16 v[42:45], v[182:185], v[190:193], v[42:45]
	v_mfma_f32_16x16x32_bf16 v[34:37], v[174:177], v[198:201], v[34:37]
	v_mfma_f32_16x16x32_bf16 v[26:29], v[182:185], v[198:201], v[26:29]
	v_mfma_f32_16x16x32_bf16 v[18:21], v[174:177], v[206:209], v[18:21]
	v_mfma_f32_16x16x32_bf16 v[10:13], v[182:185], v[206:209], v[10:13]
	v_mfma_f32_16x16x32_bf16 v[6:9], v[174:177], v[214:217], v[6:9]
	v_mfma_f32_16x16x32_bf16 v[2:5], v[182:185], v[214:217], v[2:5]
	s_setprio 0
	s_barrier
	s_movk_i32 s26, 0x100
	s_andn2_b64 vcc, exec, s[22:23]
	s_mov_b64 s[24:25], -1
	s_mov_b64 s[22:23], 0
	s_cbranch_vccz .LBB0_560
	s_and_b64 vcc, exec, s[14:15]
	s_cbranch_vccz .LBB0_563
	s_barrier

; #define PG8_STAGE(bufoff, gbase, voff) do { _Pragma("unroll") for (int _i = 0; _i < 2; ++_i) \
;         __builtin_amdgcn_global_load_lds((const unsigned*)((const char*)(gbase) + (voff)[_i]), (LAS unsigned*)(lds + (bufoff) + ldsw + _i * 8192), 16, 0, 0); } while (0)
; #define PG8_LDA(dst, b, h) do { _Pragma("unroll") for (int m = 0; m < 4; ++m) _Pragma("unroll") for (int k = 0; k < 2; ++k) dst[m][k] = *(const LAS bf16x8*)(lds + PG8_SA(b, h) + aoff + m * 2048 + k * 1024); } while (0)
; #define PG8_LDB(dst, b, h) do { _Pragma("unroll") for (int n = 0; n < 2; ++n) _Pragma("unroll") for (int k = 0; k < 2; ++k) dst[n][k] = *(const LAS bf16x8*)(lds + PG8_SB(b, h) + boff + n * 2048 + k * 1024); } while (0)
; #define PG8_MMA(ai, bj, At, Bt) do { __builtin_amdgcn_s_setprio(1); _Pragma("unroll") for (int m = 0; m < 4; ++m) _Pragma("unroll") for (int n = 0; n < 2; ++n) _Pragma("unroll") for (int k = 0; k < 2; ++k) \
;         acc[ai][bj][m][n] = __builtin_amdgcn_mfma_f32_16x16x32_bf16(Bt[n][k], At[m][k], acc[ai][bj][m][n], 0, 0, 0); __builtin_amdgcn_s_setprio(0); } while (0)
; #define PG8_WAIT_V(n) asm volatile("s_waitcnt vmcnt(" #n ")" ::: "memory")
; #define PG8_WAIT_L(n) asm volatile("s_waitcnt lgkmcnt(" #n ")" ::: "memory")
; template <class Epi, class Sched, bool ALIGN_EPI = false, bool SP2 = false>
; __device__ __forceinline__ void gemm_phase(LAS unsigned char* lds, const Gemm g, const Sched& S, const Epi& E) {
;     ...
;         for (int t = 0; t < nt; t += 2) {
;             const bool last = (t == nt - 2);
;             const char* a1 = cA + (size_t)(t + 1) * kstep;
;             const char* a2 = last ? nA : cA + (size_t)(t + 2) * kstep; const char* b2 = last ? nB : cB + (size_t)(t + 2) * kstep;
;             const char* a3 = a2 + kstep; const char* b3 = b2 + kstep;
;             if (last && has_next) S.a_ready(nxt);
;             if constexpr (SP2) {
;             PG8_LDB(B0, 0, 0); PG8_LDB(B1, 0, 1); PG8_SCHED; PG8_LDA(At, 0, 0); PG8_STAGE(PG8_SA(1, 1), a1 + hstepA, voffA);
;             PG8_WAIT_V(8); PG8_WAIT_L(0); PG8_BAR; PG8_MMA(0, 0, At, B0); PG8_MMA(0, 1, At, B1); PG8_BAR; PG8_SCHED;
;             PG8_LDA(At, 0, 1); PG8_STAGE(PG8_SB(0, 0), b2, voffB); PG8_STAGE(PG8_SB(0, 1), b2 + hstepB, voffB); PG8_STAGE(PG8_SA(0, 0), a2, voffA);
;             PG8_WAIT_V(8); PG8_WAIT_L(0); PG8_BAR; PG8_MMA(1, 0, At, B0); PG8_MMA(1, 1, At, B1); PG8_BAR; PG8_SCHED;
.LBB0_588:
	s_add_u32 s27, s20, s26
	s_addc_u32 s34, s21, 0
	s_add_u32 s30, s27, 0x100
	s_addc_u32 s31, s34, 0
	s_and_b64 s[28:29], s[24:25], exec
	s_cselect_b32 s29, s1, s31
	s_cselect_b32 s28, s0, s30
	s_add_u32 s26, s18, s26
	s_addc_u32 s30, s19, 0
	s_add_u32 s26, s26, 0x100
	s_addc_u32 s30, s30, 0
	s_and_b64 s[24:25], s[24:25], exec
	s_cselect_b32 s31, s17, s30
	s_cselect_b32 s30, s16, s26
	s_add_u32 s36, s27, 0x18080
	ds_read_b128 v[148:151], v142
	ds_read_b128 v[154:157], v142 offset:1024
	ds_read_b128 v[158:161], v142 offset:2048
	ds_read_b128 v[162:165], v142 offset:3072
	ds_read_b128 v[166:169], v143
	ds_read_b128 v[170:173], v143 offset:1024
	ds_read_b128 v[174:177], v143 offset:2048
	ds_read_b128 v[178:181], v143 offset:3072
	s_addc_u32 s37, s34, 0
	s_add_i32 s77, s56, s44
	s_add_i32 m0, s45, 0xc000
	s_add_i32 s78, s45, 0xe000
	s_add_i32 s72, s77, 0x2000
	s_add_u32 s34, s30, 0x18000
	s_addc_u32 s35, s31, 0
	s_add_i32 s76, s57, s44
	s_add_i32 s73, s76, 0x2000
	s_add_u32 s26, s28, 0x18000
	s_addc_u32 s27, s29, 0
	s_add_i32 s71, s59, s44
	s_add_i32 s67, s71, 0x2000
	s_add_u32 s24, s30, 0x18080
	s_addc_u32 s25, s31, 0
	s_add_i32 s70, s60, s44
	s_add_i32 s66, s70, 0x2000
	v_lshl_add_u64 v[214:215], s[36:37], 0, v[130:131]
	ds_read_b128 v[182:185], v144
	ds_read_b128 v[186:189], v144 offset:1024
	ds_read_b128 v[190:193], v144 offset:2048
	ds_read_b128 v[194:197], v144 offset:3072
	ds_read_b128 v[198:201], v144 offset:4096
	ds_read_b128 v[202:205], v144 offset:5120
	ds_read_b128 v[206:209], v144 offset:6144
	ds_read_b128 v[210:213], v144 offset:7168
	global_load_lds_dwordx4 v[214:215], off
	v_lshl_add_u64 v[214:215], s[36:37], 0, v[134:135]
	s_mov_b32 m0, s78
	s_nop 0
	global_load_lds_dwordx4 v[214:215], off
	s_waitcnt vmcnt(8)
	s_waitcnt lgkmcnt(0)
	s_setprio 1
	s_barrier
	v_mfma_f32_16x16x32_bf16 v[126:129], v[148:151], v[182:185], v[126:129]
	v_mfma_f32_16x16x32_bf16 v[122:125], v[158:161], v[182:185], v[122:125]
	v_mfma_f32_16x16x32_bf16 v[118:121], v[148:151], v[190:193], v[118:121]
	v_mfma_f32_16x16x32_bf16 v[110:113], v[158:161], v[190:193], v[110:113]
	v_mfma_f32_16x16x32_bf16 v[102:105], v[148:151], v[198:201], v[102:105]
	v_mfma_f32_16x16x32_bf16 v[94:97], v[158:161], v[198:201], v[94:97]
	v_mfma_f32_16x16x32_bf16 v[86:89], v[148:151], v[206:209], v[86:89]
	v_mfma_f32_16x16x32_bf16 v[78:81], v[158:161], v[206:209], v[78:81]
	v_mfma_f32_16x16x32_bf16 v[126:129], v[154:157], v[186:189], v[126:129]
	v_mfma_f32_16x16x32_bf16 v[122:125], v[162:165], v[186:189], v[122:125]
	v_mfma_f32_16x16x32_bf16 v[118:121], v[154:157], v[194:197], v[118:121]
	v_mfma_f32_16x16x32_bf16 v[110:113], v[162:165], v[194:197], v[110:113]
	v_mfma_f32_16x16x32_bf16 v[102:105], v[154:157], v[202:205], v[102:105]
	v_mfma_f32_16x16x32_bf16 v[94:97], v[162:165], v[202:205], v[94:97]
	v_mfma_f32_16x16x32_bf16 v[86:89], v[154:157], v[210:213], v[86:89]
	v_mfma_f32_16x16x32_bf16 v[78:81], v[162:165], v[210:213], v[78:81]
	s_setprio 0
	s_setprio 1
	v_mfma_f32_16x16x32_bf16 v[114:117], v[166:169], v[182:185], v[114:117]
	v_mfma_f32_16x16x32_bf16 v[106:109], v[174:177], v[182:185], v[106:109]
	v_mfma_f32_16x16x32_bf16 v[98:101], v[166:169], v[190:193], v[98:101]
	v_mfma_f32_16x16x32_bf16 v[90:93], v[174:177], v[190:193], v[90:93]
	v_mfma_f32_16x16x32_bf16 v[82:85], v[166:169], v[198:201], v[82:85]
	v_mfma_f32_16x16x32_bf16 v[74:77], v[174:177], v[198:201], v[74:77]
	v_mfma_f32_16x16x32_bf16 v[70:73], v[166:169], v[206:209], v[70:73]
	v_mfma_f32_16x16x32_bf16 v[66:69], v[174:177], v[206:209], v[66:69]
	v_mfma_f32_16x16x32_bf16 v[114:117], v[170:173], v[186:189], v[114:117]
	v_mfma_f32_16x16x32_bf16 v[106:109], v[178:181], v[186:189], v[106:109]
	v_mfma_f32_16x16x32_bf16 v[98:101], v[170:173], v[194:197], v[98:101]
	v_mfma_f32_16x16x32_bf16 v[90:93], v[178:181], v[194:197], v[90:93]
	v_mfma_f32_16x16x32_bf16 v[82:85], v[170:173], v[202:205], v[82:85]
	v_mfma_f32_16x16x32_bf16 v[74:77], v[178:181], v[202:205], v[74:77]
	v_mfma_f32_16x16x32_bf16 v[70:73], v[170:173], v[210:213], v[70:73]
	v_mfma_f32_16x16x32_bf16 v[66:69], v[178:181], v[210:213], v[66:69]
	s_setprio 0
	s_barrier
	s_mov_b32 m0, s77
	v_lshl_add_u64 v[214:215], s[30:31], 0, v[132:133]
	ds_read_b128 v[182:185], v144 offset:16384
	ds_read_b128 v[186:189], v144 offset:17408
	ds_read_b128 v[190:193], v144 offset:18432
	ds_read_b128 v[194:197], v144 offset:19456
	ds_read_b128 v[198:201], v144 offset:20480
	ds_read_b128 v[202:205], v144 offset:21504
	ds_read_b128 v[206:209], v144 offset:22528
	ds_read_b128 v[210:213], v144 offset:23552
	global_load_lds_dwordx4 v[214:215], off
	v_lshl_add_u64 v[216:217], s[30:31], 0, v[136:137]
	s_mov_b32 m0, s72
	v_lshl_add_u64 v[218:219], s[34:35], 0, v[132:133]
	global_load_lds_dwordx4 v[216:217], off
	s_mov_b32 m0, s76
	v_lshl_add_u64 v[220:221], s[28:29], 0, v[134:135]
	global_load_lds_dwordx4 v[218:219], off
	v_lshl_add_u64 v[218:219], s[34:35], 0, v[136:137]
	s_mov_b32 m0, s73
	s_nop 0
	global_load_lds_dwordx4 v[218:219], off
	v_lshl_add_u64 v[218:219], s[28:29], 0, v[130:131]
	s_mov_b32 m0, s45
	s_nop 0
	global_load_lds_dwordx4 v[218:219], off
	s_mov_b32 m0, s46
	s_nop 0
	global_load_lds_dwordx4 v[220:221], off
	s_waitcnt vmcnt(8)
	s_waitcnt lgkmcnt(0)
	s_setprio 1
	s_barrier
; #define PG8_STAGE(bufoff, gbase, voff) do { _Pragma("unroll") for (int _i = 0; _i < 2; ++_i) \
;         __builtin_amdgcn_global_load_lds((const unsigned*)((const char*)(gbase) + (voff)[_i]), (LAS unsigned*)(lds + (bufoff) + ldsw + _i * 8192), 16, 0, 0); } while (0)
; #define PG8_LDA(dst, b, h) do { _Pragma("unroll") for (int m = 0; m < 4; ++m) _Pragma("unroll") for (int k = 0; k < 2; ++k) dst[m][k] = *(const LAS bf16x8*)(lds + PG8_SA(b, h) + aoff + m * 2048 + k * 1024); } while (0)
; #define PG8_LDB(dst, b, h) do { _Pragma("unroll") for (int n = 0; n < 2; ++n) _Pragma("unroll") for (int k = 0; k < 2; ++k) dst[n][k] = *(const LAS bf16x8*)(lds + PG8_SB(b, h) + boff + n * 2048 + k * 1024); } while (0)
; #define PG8_MMA(ai, bj, At, Bt) do { __builtin_amdgcn_s_setprio(1); _Pragma("unroll") for (int m = 0; m < 4; ++m) _Pragma("unroll") for (int n = 0; n < 2; ++n) _Pragma("unroll") for (int k = 0; k < 2; ++k) \
;         acc[ai][bj][m][n] = __builtin_amdgcn_mfma_f32_16x16x32_bf16(Bt[n][k], At[m][k], acc[ai][bj][m][n], 0, 0, 0); __builtin_amdgcn_s_setprio(0); } while (0)
; #define PG8_WAIT_V(n) asm volatile("s_waitcnt vmcnt(" #n ")" ::: "memory")
; #define PG8_WAIT_L(n) asm volatile("s_waitcnt lgkmcnt(" #n ")" ::: "memory")
; #define PG8_BAR __builtin_amdgcn_s_barrier()
; #define PG8_SCHED __builtin_amdgcn_sched_barrier(0)
; template <class Epi, class Sched, bool ALIGN_EPI = false, bool SP2 = false>
; __device__ __forceinline__ void gemm_phase(LAS unsigned char* lds, const Gemm g, const Sched& S, const Epi& E) {
;     ...
;             PG8_WAIT_V(8); PG8_WAIT_L(0); PG8_BAR; PG8_MMA(1, 0, At, B0); PG8_MMA(1, 1, At, B1); PG8_BAR; PG8_SCHED;
;             PG8_LDB(B0, 1, 0); PG8_LDB(B1, 1, 1); PG8_SCHED; PG8_LDA(At, 1, 0); PG8_STAGE(PG8_SA(0, 1), a2 + hstepA, voffA);
;             PG8_WAIT_V(8); PG8_WAIT_L(0); PG8_BAR; PG8_MMA(0, 0, At, B0); PG8_MMA(0, 1, At, B1); PG8_BAR; PG8_SCHED;
	v_mfma_f32_16x16x32_bf16 v[62:65], v[148:151], v[182:185], v[62:65]
	v_mfma_f32_16x16x32_bf16 v[58:61], v[158:161], v[182:185], v[58:61]
	v_mfma_f32_16x16x32_bf16 v[54:57], v[148:151], v[190:193], v[54:57]
	v_mfma_f32_16x16x32_bf16 v[46:49], v[158:161], v[190:193], v[46:49]
	v_mfma_f32_16x16x32_bf16 v[38:41], v[148:151], v[198:201], v[38:41]
	v_mfma_f32_16x16x32_bf16 v[30:33], v[158:161], v[198:201], v[30:33]
	v_mfma_f32_16x16x32_bf16 v[22:25], v[148:151], v[206:209], v[22:25]
	v_mfma_f32_16x16x32_bf16 v[14:17], v[158:161], v[206:209], v[14:17]
	v_mfma_f32_16x16x32_bf16 v[62:65], v[154:157], v[186:189], v[62:65]
	v_mfma_f32_16x16x32_bf16 v[58:61], v[162:165], v[186:189], v[58:61]
	v_mfma_f32_16x16x32_bf16 v[54:57], v[154:157], v[194:197], v[54:57]
	v_mfma_f32_16x16x32_bf16 v[46:49], v[162:165], v[194:197], v[46:49]
	v_mfma_f32_16x16x32_bf16 v[38:41], v[154:157], v[202:205], v[38:41]
	v_mfma_f32_16x16x32_bf16 v[30:33], v[162:165], v[202:205], v[30:33]
	v_mfma_f32_16x16x32_bf16 v[22:25], v[154:157], v[210:213], v[22:25]
	v_mfma_f32_16x16x32_bf16 v[14:17], v[162:165], v[210:213], v[14:17]
	s_setprio 0
	s_setprio 1
	v_mfma_f32_16x16x32_bf16 v[50:53], v[166:169], v[182:185], v[50:53]
	v_mfma_f32_16x16x32_bf16 v[42:45], v[174:177], v[182:185], v[42:45]
	v_mfma_f32_16x16x32_bf16 v[34:37], v[166:169], v[190:193], v[34:37]
	v_mfma_f32_16x16x32_bf16 v[26:29], v[174:177], v[190:193], v[26:29]
	v_mfma_f32_16x16x32_bf16 v[18:21], v[166:169], v[198:201], v[18:21]
	v_mfma_f32_16x16x32_bf16 v[10:13], v[174:177], v[198:201], v[10:13]
	v_mfma_f32_16x16x32_bf16 v[6:9], v[166:169], v[206:209], v[6:9]
	v_mfma_f32_16x16x32_bf16 v[2:5], v[174:177], v[206:209], v[2:5]
	v_mfma_f32_16x16x32_bf16 v[50:53], v[170:173], v[186:189], v[50:53]
	v_mfma_f32_16x16x32_bf16 v[42:45], v[178:181], v[186:189], v[42:45]
	v_mfma_f32_16x16x32_bf16 v[34:37], v[170:173], v[194:197], v[34:37]
	v_mfma_f32_16x16x32_bf16 v[26:29], v[178:181], v[194:197], v[26:29]
	v_mfma_f32_16x16x32_bf16 v[18:21], v[170:173], v[202:205], v[18:21]
	v_mfma_f32_16x16x32_bf16 v[10:13], v[178:181], v[202:205], v[10:13]
	v_mfma_f32_16x16x32_bf16 v[6:9], v[170:173], v[210:213], v[6:9]
	v_mfma_f32_16x16x32_bf16 v[2:5], v[178:181], v[210:213], v[2:5]
	s_setprio 0
	s_barrier
	ds_read_b128 v[148:151], v146
	ds_read_b128 v[154:157], v146 offset:1024
	ds_read_b128 v[158:161], v146 offset:2048
	ds_read_b128 v[162:165], v146 offset:3072
	ds_read_b128 v[166:169], v147
	ds_read_b128 v[170:173], v147 offset:1024
	ds_read_b128 v[174:177], v147 offset:2048
	ds_read_b128 v[178:181], v147 offset:3072
	s_mov_b32 m0, s47
	v_lshl_add_u64 v[222:223], s[26:27], 0, v[130:131]
	ds_read_b128 v[182:185], v144 offset:32768
	ds_read_b128 v[186:189], v144 offset:33792
	ds_read_b128 v[190:193], v144 offset:34816
	ds_read_b128 v[194:197], v144 offset:35840
	ds_read_b128 v[198:201], v144 offset:36864
	ds_read_b128 v[202:205], v144 offset:37888
	ds_read_b128 v[206:209], v144 offset:38912
	ds_read_b128 v[210:213], v144 offset:39936
	global_load_lds_dwordx4 v[222:223], off
	v_lshl_add_u64 v[222:223], s[26:27], 0, v[134:135]
	s_mov_b32 m0, s50
	s_nop 0
	global_load_lds_dwordx4 v[222:223], off
	s_waitcnt vmcnt(8)
	s_waitcnt lgkmcnt(0)
	s_setprio 1
	s_barrier
	v_mfma_f32_16x16x32_bf16 v[126:129], v[148:151], v[182:185], v[126:129]
	v_mfma_f32_16x16x32_bf16 v[122:125], v[158:161], v[182:185], v[122:125]
	v_mfma_f32_16x16x32_bf16 v[118:121], v[148:151], v[190:193], v[118:121]
	v_mfma_f32_16x16x32_bf16 v[110:113], v[158:161], v[190:193], v[110:113]
	v_mfma_f32_16x16x32_bf16 v[102:105], v[148:151], v[198:201], v[102:105]
	v_mfma_f32_16x16x32_bf16 v[94:97], v[158:161], v[198:201], v[94:97]
	v_mfma_f32_16x16x32_bf16 v[86:89], v[148:151], v[206:209], v[86:89]
	v_mfma_f32_16x16x32_bf16 v[78:81], v[158:161], v[206:209], v[78:81]
	v_mfma_f32_16x16x32_bf16 v[126:129], v[154:157], v[186:189], v[126:129]
	v_mfma_f32_16x16x32_bf16 v[122:125], v[162:165], v[186:189], v[122:125]
	v_mfma_f32_16x16x32_bf16 v[118:121], v[154:157], v[194:197], v[118:121]
	v_mfma_f32_16x16x32_bf16 v[110:113], v[162:165], v[194:197], v[110:113]
	v_mfma_f32_16x16x32_bf16 v[102:105], v[154:157], v[202:205], v[102:105]
	v_mfma_f32_16x16x32_bf16 v[94:97], v[162:165], v[202:205], v[94:97]
	v_mfma_f32_16x16x32_bf16 v[86:89], v[154:157], v[210:213], v[86:89]
	v_mfma_f32_16x16x32_bf16 v[78:81], v[162:165], v[210:213], v[78:81]
	s_setprio 0
	s_setprio 1
	v_mfma_f32_16x16x32_bf16 v[114:117], v[166:169], v[182:185], v[114:117]
	v_mfma_f32_16x16x32_bf16 v[106:109], v[174:177], v[182:185], v[106:109]
	v_mfma_f32_16x16x32_bf16 v[98:101], v[166:169], v[190:193], v[98:101]
	v_mfma_f32_16x16x32_bf16 v[90:93], v[174:177], v[190:193], v[90:93]
	v_mfma_f32_16x16x32_bf16 v[82:85], v[166:169], v[198:201], v[82:85]
	v_mfma_f32_16x16x32_bf16 v[74:77], v[174:177], v[198:201], v[74:77]
	v_mfma_f32_16x16x32_bf16 v[70:73], v[166:169], v[206:209], v[70:73]
	v_mfma_f32_16x16x32_bf16 v[66:69], v[174:177], v[206:209], v[66:69]
	v_mfma_f32_16x16x32_bf16 v[114:117], v[170:173], v[186:189], v[114:117]
	v_mfma_f32_16x16x32_bf16 v[106:109], v[178:181], v[186:189], v[106:109]
	v_mfma_f32_16x16x32_bf16 v[98:101], v[170:173], v[194:197], v[98:101]
	v_mfma_f32_16x16x32_bf16 v[90:93], v[178:181], v[194:197], v[90:93]
	v_mfma_f32_16x16x32_bf16 v[82:85], v[170:173], v[202:205], v[82:85]
	v_mfma_f32_16x16x32_bf16 v[74:77], v[178:181], v[202:205], v[74:77]
	v_mfma_f32_16x16x32_bf16 v[70:73], v[170:173], v[210:213], v[70:73]
	v_mfma_f32_16x16x32_bf16 v[66:69], v[178:181], v[210:213], v[66:69]
	s_setprio 0
	s_barrier
; #define PG8_STAGE(bufoff, gbase, voff) do { _Pragma("unroll") for (int _i = 0; _i < 2; ++_i) \
;         __builtin_amdgcn_global_load_lds((const unsigned*)((const char*)(gbase) + (voff)[_i]), (LAS unsigned*)(lds + (bufoff) + ldsw + _i * 8192), 16, 0, 0); } while (0)
; #define PG8_LDA(dst, b, h) do { _Pragma("unroll") for (int m = 0; m < 4; ++m) _Pragma("unroll") for (int k = 0; k < 2; ++k) dst[m][k] = *(const LAS bf16x8*)(lds + PG8_SA(b, h) + aoff + m * 2048 + k * 1024); } while (0)
; #define PG8_MMA(ai, bj, At, Bt) do { __builtin_amdgcn_s_setprio(1); _Pragma("unroll") for (int m = 0; m < 4; ++m) _Pragma("unroll") for (int n = 0; n < 2; ++n) _Pragma("unroll") for (int k = 0; k < 2; ++k) \
;         acc[ai][bj][m][n] = __builtin_amdgcn_mfma_f32_16x16x32_bf16(Bt[n][k], At[m][k], acc[ai][bj][m][n], 0, 0, 0); __builtin_amdgcn_s_setprio(0); } while (0)
; #define PG8_WAIT_V(n) asm volatile("s_waitcnt vmcnt(" #n ")" ::: "memory")
; #define PG8_WAIT_L(n) asm volatile("s_waitcnt lgkmcnt(" #n ")" ::: "memory")
; #define PG8_BAR __builtin_amdgcn_s_barrier()
; #define PG8_SCHED __builtin_amdgcn_sched_barrier(0)
; template <class Epi, class Sched, bool ALIGN_EPI = false, bool SP2 = false>
; __device__ __forceinline__ void gemm_phase(LAS unsigned char* lds, const Gemm g, const Sched& S, const Epi& E) {
;     ...
;         for (int t = 0; t < nt; t += 2) {
;     ...
;             PG8_LDA(At, 1, 1); PG8_STAGE(PG8_SB(1, 0), b3, voffB); PG8_STAGE(PG8_SB(1, 1), b3 + hstepB, voffB); PG8_STAGE(PG8_SA(1, 0), a3, voffA);
;             PG8_WAIT_V(8); PG8_WAIT_L(0); PG8_BAR; PG8_MMA(1, 0, At, B0); PG8_MMA(1, 1, At, B1); PG8_BAR; PG8_SCHED;
	s_mov_b32 m0, s71
	v_lshl_add_u64 v[214:215], v[214:215], 0, s[12:13]
	ds_read_b128 v[182:185], v144 offset:49152
	ds_read_b128 v[186:189], v144 offset:50176
	ds_read_b128 v[190:193], v144 offset:51200
	ds_read_b128 v[194:197], v144 offset:52224
	ds_read_b128 v[198:201], v144 offset:53248
	ds_read_b128 v[202:205], v144 offset:54272
	ds_read_b128 v[206:209], v144 offset:55296
	ds_read_b128 v[210:213], v144 offset:56320
	global_load_lds_dwordx4 v[214:215], off
	v_lshl_add_u64 v[214:215], v[216:217], 0, s[12:13]
	s_mov_b32 m0, s67
	s_nop 0
	global_load_lds_dwordx4 v[214:215], off
	v_lshl_add_u64 v[214:215], s[24:25], 0, v[132:133]
	s_mov_b32 m0, s70
	s_nop 0
	global_load_lds_dwordx4 v[214:215], off
	v_lshl_add_u64 v[214:215], s[24:25], 0, v[136:137]
	s_mov_b32 m0, s66
	s_nop 0
	global_load_lds_dwordx4 v[214:215], off
	v_lshl_add_u64 v[214:215], v[218:219], 0, s[12:13]
	s_mov_b32 m0, s51
	s_nop 0
	global_load_lds_dwordx4 v[214:215], off
	v_lshl_add_u64 v[214:215], v[220:221], 0, s[12:13]
	s_mov_b32 m0, s52
	s_nop 0
	global_load_lds_dwordx4 v[214:215], off
	s_waitcnt vmcnt(8)
	s_waitcnt lgkmcnt(0)
	s_setprio 1
	s_barrier
	v_mfma_f32_16x16x32_bf16 v[62:65], v[148:151], v[182:185], v[62:65]
	v_mfma_f32_16x16x32_bf16 v[58:61], v[158:161], v[182:185], v[58:61]
	v_mfma_f32_16x16x32_bf16 v[54:57], v[148:151], v[190:193], v[54:57]
	v_mfma_f32_16x16x32_bf16 v[46:49], v[158:161], v[190:193], v[46:49]
	v_mfma_f32_16x16x32_bf16 v[38:41], v[148:151], v[198:201], v[38:41]
	v_mfma_f32_16x16x32_bf16 v[30:33], v[158:161], v[198:201], v[30:33]
	v_mfma_f32_16x16x32_bf16 v[22:25], v[148:151], v[206:209], v[22:25]
	v_mfma_f32_16x16x32_bf16 v[14:17], v[158:161], v[206:209], v[14:17]
	v_mfma_f32_16x16x32_bf16 v[62:65], v[154:157], v[186:189], v[62:65]
	v_mfma_f32_16x16x32_bf16 v[58:61], v[162:165], v[186:189], v[58:61]
	v_mfma_f32_16x16x32_bf16 v[54:57], v[154:157], v[194:197], v[54:57]
	v_mfma_f32_16x16x32_bf16 v[46:49], v[162:165], v[194:197], v[46:49]
	v_mfma_f32_16x16x32_bf16 v[38:41], v[154:157], v[202:205], v[38:41]
	v_mfma_f32_16x16x32_bf16 v[30:33], v[162:165], v[202:205], v[30:33]
	v_mfma_f32_16x16x32_bf16 v[22:25], v[154:157], v[210:213], v[22:25]
	v_mfma_f32_16x16x32_bf16 v[14:17], v[162:165], v[210:213], v[14:17]
	s_setprio 0
	s_setprio 1
	v_mfma_f32_16x16x32_bf16 v[50:53], v[166:169], v[182:185], v[50:53]
	v_mfma_f32_16x16x32_bf16 v[42:45], v[174:177], v[182:185], v[42:45]
	v_mfma_f32_16x16x32_bf16 v[34:37], v[166:169], v[190:193], v[34:37]
	v_mfma_f32_16x16x32_bf16 v[26:29], v[174:177], v[190:193], v[26:29]
	v_mfma_f32_16x16x32_bf16 v[18:21], v[166:169], v[198:201], v[18:21]
	v_mfma_f32_16x16x32_bf16 v[10:13], v[174:177], v[198:201], v[10:13]
	v_mfma_f32_16x16x32_bf16 v[6:9], v[166:169], v[206:209], v[6:9]
	v_mfma_f32_16x16x32_bf16 v[2:5], v[174:177], v[206:209], v[2:5]
	v_mfma_f32_16x16x32_bf16 v[50:53], v[170:173], v[186:189], v[50:53]
	v_mfma_f32_16x16x32_bf16 v[42:45], v[178:181], v[186:189], v[42:45]
	v_mfma_f32_16x16x32_bf16 v[34:37], v[170:173], v[194:197], v[34:37]
	v_mfma_f32_16x16x32_bf16 v[26:29], v[178:181], v[194:197], v[26:29]
	v_mfma_f32_16x16x32_bf16 v[18:21], v[170:173], v[202:205], v[18:21]
	v_mfma_f32_16x16x32_bf16 v[10:13], v[178:181], v[202:205], v[10:13]
	v_mfma_f32_16x16x32_bf16 v[6:9], v[170:173], v[210:213], v[6:9]
	v_mfma_f32_16x16x32_bf16 v[2:5], v[178:181], v[210:213], v[2:5]
	s_setprio 0
	s_barrier
	s_movk_i32 s26, 0x100
	s_andn2_b64 vcc, exec, s[22:23]
	s_mov_b64 s[24:25], -1
	s_mov_b64 s[22:23], 0
	s_cbranch_vccz .LBB0_588
	s_and_b64 vcc, exec, s[14:15]
	s_cbranch_vccz .LBB0_591
	s_barrier

; #define PG8_STAGE(bufoff, gbase, voff) do { _Pragma("unroll") for (int _i = 0; _i < 2; ++_i) \
;         __builtin_amdgcn_global_load_lds((const unsigned*)((const char*)(gbase) + (voff)[_i]), (LAS unsigned*)(lds + (bufoff) + ldsw + _i * 8192), 16, 0, 0); } while (0)
; #define PG8_LDA(dst, b, h) do { _Pragma("unroll") for (int m = 0; m < 4; ++m) _Pragma("unroll") for (int k = 0; k < 2; ++k) dst[m][k] = *(const LAS bf16x8*)(lds + PG8_SA(b, h) + aoff + m * 2048 + k * 1024); } while (0)
; #define PG8_LDB(dst, b, h) do { _Pragma("unroll") for (int n = 0; n < 2; ++n) _Pragma("unroll") for (int k = 0; k < 2; ++k) dst[n][k] = *(const LAS bf16x8*)(lds + PG8_SB(b, h) + boff + n * 2048 + k * 1024); } while (0)
; #define PG8_MMA(ai, bj, At, Bt) do { __builtin_amdgcn_s_setprio(1); _Pragma("unroll") for (int m = 0; m < 4; ++m) _Pragma("unroll") for (int n = 0; n < 2; ++n) _Pragma("unroll") for (int k = 0; k < 2; ++k) \
;         acc[ai][bj][m][n] = __builtin_amdgcn_mfma_f32_16x16x32_bf16(Bt[n][k], At[m][k], acc[ai][bj][m][n], 0, 0, 0); __builtin_amdgcn_s_setprio(0); } while (0)
; #define PG8_WAIT_V(n) asm volatile("s_waitcnt vmcnt(" #n ")" ::: "memory")
; #define PG8_WAIT_L(n) asm volatile("s_waitcnt lgkmcnt(" #n ")" ::: "memory")
; #define PG8_BAR __builtin_amdgcn_s_barrier()
; template <class Epi, class Sched, bool ALIGN_EPI = false, bool SP2 = false>
; __device__ __forceinline__ void gemm_phase(LAS unsigned char* lds, const Gemm g, const Sched& S, const Epi& E) {
;     ...
;             const bool last = (t == nt - 2);
;             const char* a1 = cA + (size_t)(t + 1) * kstep;
;             const char* a2 = last ? nA : cA + (size_t)(t + 2) * kstep; const char* b2 = last ? nB : cB + (size_t)(t + 2) * kstep;
;             const char* a3 = a2 + kstep; const char* b3 = b2 + kstep;
;             if (last && has_next) S.a_ready(nxt);
;             if constexpr (SP2) {
;             PG8_LDB(B0, 0, 0); PG8_LDB(B1, 0, 1); PG8_SCHED; PG8_LDA(At, 0, 0); PG8_STAGE(PG8_SA(1, 1), a1 + hstepA, voffA);
;             PG8_WAIT_V(8); PG8_WAIT_L(0); PG8_BAR; PG8_MMA(0, 0, At, B0); PG8_MMA(0, 1, At, B1); PG8_BAR; PG8_SCHED;
;             PG8_LDA(At, 0, 1); PG8_STAGE(PG8_SB(0, 0), b2, voffB); PG8_STAGE(PG8_SB(0, 1), b2 + hstepB, voffB); PG8_STAGE(PG8_SA(0, 0), a2, voffA);
;             PG8_WAIT_V(8); PG8_WAIT_L(0); PG8_BAR; PG8_MMA(1, 0, At, B0); PG8_MMA(1, 1, At, B1); PG8_BAR; PG8_SCHED;
.LBB0_968:
	ds_read_b128 v[120:123], v221
	ds_read_b128 v[124:127], v221 offset:1024
	ds_read_b128 v[136:139], v221 offset:2048
	ds_read_b128 v[140:143], v221 offset:3072
	ds_read_b128 v[144:147], v222
	ds_read_b128 v[148:151], v222 offset:1024
	ds_read_b128 v[170:173], v222 offset:2048
	ds_read_b128 v[174:177], v222 offset:3072
	s_add_u32 s28, s26, 0xfff80080
	s_addc_u32 s29, s27, -1
	s_cmp_eq_u32 s50, 28
	s_cselect_b32 s31, s17, s29
	s_cselect_b32 s30, s23, s28
	s_cselect_b32 s29, s15, s49
	s_cselect_b32 s28, s25, s33
	v_lshl_add_u64 v[210:211], s[26:27], 0, v[162:163]
	s_add_i32 m0, s35, 0xc000
	ds_read_b128 v[178:181], v223
	ds_read_b128 v[182:185], v223 offset:1024
	ds_read_b128 v[186:189], v223 offset:2048
	ds_read_b128 v[190:193], v223 offset:3072
	ds_read_b128 v[194:197], v223 offset:4096
	ds_read_b128 v[198:201], v223 offset:5120
	ds_read_b128 v[202:205], v223 offset:6144
	ds_read_b128 v[206:209], v223 offset:7168
	global_load_lds_dwordx4 v[210:211], off
	v_lshl_add_u64 v[210:211], s[26:27], 0, v[164:165]
	s_add_i32 m0, s35, 0xe000
	s_nop 0
	global_load_lds_dwordx4 v[210:211], off
	s_waitcnt vmcnt(8)
	s_waitcnt lgkmcnt(0)
	s_setprio 1
	s_barrier
	v_mfma_f32_16x16x32_bf16 v[132:135], v[120:123], v[178:181], v[132:135]
	v_mfma_f32_16x16x32_bf16 v[128:131], v[136:139], v[178:181], v[128:131]
	v_mfma_f32_16x16x32_bf16 v[100:103], v[120:123], v[186:189], v[100:103]
	v_mfma_f32_16x16x32_bf16 v[96:99], v[136:139], v[186:189], v[96:99]
	v_mfma_f32_16x16x32_bf16 v[116:119], v[120:123], v[194:197], v[116:119]
	v_mfma_f32_16x16x32_bf16 v[112:115], v[136:139], v[194:197], v[112:115]
	v_mfma_f32_16x16x32_bf16 v[108:111], v[120:123], v[202:205], v[108:111]
	v_mfma_f32_16x16x32_bf16 v[104:107], v[136:139], v[202:205], v[104:107]
	v_mfma_f32_16x16x32_bf16 v[132:135], v[124:127], v[182:185], v[132:135]
	v_mfma_f32_16x16x32_bf16 v[128:131], v[140:143], v[182:185], v[128:131]
	v_mfma_f32_16x16x32_bf16 v[100:103], v[124:127], v[190:193], v[100:103]
	v_mfma_f32_16x16x32_bf16 v[96:99], v[140:143], v[190:193], v[96:99]
	v_mfma_f32_16x16x32_bf16 v[116:119], v[124:127], v[198:201], v[116:119]
	v_mfma_f32_16x16x32_bf16 v[112:115], v[140:143], v[198:201], v[112:115]
	v_mfma_f32_16x16x32_bf16 v[108:111], v[124:127], v[206:209], v[108:111]
	v_mfma_f32_16x16x32_bf16 v[104:107], v[140:143], v[206:209], v[104:107]
	s_setprio 0
	s_setprio 1
	v_mfma_f32_16x16x32_bf16 v[60:63], v[144:147], v[178:181], v[60:63]
	v_mfma_f32_16x16x32_bf16 v[56:59], v[170:173], v[178:181], v[56:59]
	v_mfma_f32_16x16x32_bf16 v[52:55], v[144:147], v[186:189], v[52:55]
	v_mfma_f32_16x16x32_bf16 v[48:51], v[170:173], v[186:189], v[48:51]
	v_mfma_f32_16x16x32_bf16 v[44:47], v[144:147], v[194:197], v[44:47]
	v_mfma_f32_16x16x32_bf16 v[40:43], v[170:173], v[194:197], v[40:43]
	v_mfma_f32_16x16x32_bf16 v[36:39], v[144:147], v[202:205], v[36:39]
	v_mfma_f32_16x16x32_bf16 v[32:35], v[170:173], v[202:205], v[32:35]
	v_mfma_f32_16x16x32_bf16 v[60:63], v[148:151], v[182:185], v[60:63]
	v_mfma_f32_16x16x32_bf16 v[56:59], v[174:177], v[182:185], v[56:59]
	v_mfma_f32_16x16x32_bf16 v[52:55], v[148:151], v[190:193], v[52:55]
	v_mfma_f32_16x16x32_bf16 v[48:51], v[174:177], v[190:193], v[48:51]
	v_mfma_f32_16x16x32_bf16 v[44:47], v[148:151], v[198:201], v[44:47]
	v_mfma_f32_16x16x32_bf16 v[40:43], v[174:177], v[198:201], v[40:43]
	v_mfma_f32_16x16x32_bf16 v[36:39], v[148:151], v[206:209], v[36:39]
	v_mfma_f32_16x16x32_bf16 v[32:35], v[174:177], v[206:209], v[32:35]
	s_setprio 0
	s_barrier
	s_add_i32 s51, s45, s34
	v_lshl_add_u64 v[210:211], s[28:29], 0, v[156:157]
	s_mov_b32 m0, s51
	ds_read_b128 v[178:181], v223 offset:16384
	ds_read_b128 v[182:185], v223 offset:17408
	ds_read_b128 v[186:189], v223 offset:18432
	ds_read_b128 v[190:193], v223 offset:19456
	ds_read_b128 v[194:197], v223 offset:20480
	ds_read_b128 v[198:201], v223 offset:21504
	ds_read_b128 v[202:205], v223 offset:22528
	ds_read_b128 v[206:209], v223 offset:23552
	global_load_lds_dwordx4 v[210:211], off
	s_add_i32 m0, s51, 0x2000
	s_add_u32 s52, s28, 0x80000
	v_lshl_add_u64 v[212:213], s[28:29], 0, v[160:161]
	s_addc_u32 s53, s29, 0
	s_add_i32 s51, s46, s34
	global_load_lds_dwordx4 v[212:213], off
	v_lshl_add_u64 v[214:215], s[52:53], 0, v[156:157]
	s_mov_b32 m0, s51
	v_lshl_add_u64 v[216:217], s[30:31], 0, v[158:159]
	global_load_lds_dwordx4 v[214:215], off
	v_lshl_add_u64 v[214:215], s[52:53], 0, v[160:161]
	s_add_i32 m0, s51, 0x2000
	s_nop 0
	global_load_lds_dwordx4 v[214:215], off
	v_lshl_add_u64 v[214:215], s[30:31], 0, v[154:155]
	s_mov_b32 m0, s35
	s_nop 0
	global_load_lds_dwordx4 v[214:215], off
	s_mov_b32 m0, s36
	s_nop 0
	global_load_lds_dwordx4 v[216:217], off
	s_waitcnt vmcnt(8)
	s_waitcnt lgkmcnt(0)
	s_setprio 1
	s_barrier
; #define PG8_STAGE(bufoff, gbase, voff) do { _Pragma("unroll") for (int _i = 0; _i < 2; ++_i) \
;         __builtin_amdgcn_global_load_lds((const unsigned*)((const char*)(gbase) + (voff)[_i]), (LAS unsigned*)(lds + (bufoff) + ldsw + _i * 8192), 16, 0, 0); } while (0)
; #define PG8_LDA(dst, b, h) do { _Pragma("unroll") for (int m = 0; m < 4; ++m) _Pragma("unroll") for (int k = 0; k < 2; ++k) dst[m][k] = *(const LAS bf16x8*)(lds + PG8_SA(b, h) + aoff + m * 2048 + k * 1024); } while (0)
; #define PG8_LDB(dst, b, h) do { _Pragma("unroll") for (int n = 0; n < 2; ++n) _Pragma("unroll") for (int k = 0; k < 2; ++k) dst[n][k] = *(const LAS bf16x8*)(lds + PG8_SB(b, h) + boff + n * 2048 + k * 1024); } while (0)
; #define PG8_MMA(ai, bj, At, Bt) do { __builtin_amdgcn_s_setprio(1); _Pragma("unroll") for (int m = 0; m < 4; ++m) _Pragma("unroll") for (int n = 0; n < 2; ++n) _Pragma("unroll") for (int k = 0; k < 2; ++k) \
;         acc[ai][bj][m][n] = __builtin_amdgcn_mfma_f32_16x16x32_bf16(Bt[n][k], At[m][k], acc[ai][bj][m][n], 0, 0, 0); __builtin_amdgcn_s_setprio(0); } while (0)
; #define PG8_WAIT_V(n) asm volatile("s_waitcnt vmcnt(" #n ")" ::: "memory")
; #define PG8_WAIT_L(n) asm volatile("s_waitcnt lgkmcnt(" #n ")" ::: "memory")
; #define PG8_BAR __builtin_amdgcn_s_barrier()
; #define PG8_SCHED __builtin_amdgcn_sched_barrier(0)
; template <class Epi, class Sched, bool ALIGN_EPI = false, bool SP2 = false>
; __device__ __forceinline__ void gemm_phase(LAS unsigned char* lds, const Gemm g, const Sched& S, const Epi& E) {
;     ...
;             PG8_WAIT_V(8); PG8_WAIT_L(0); PG8_BAR; PG8_MMA(1, 0, At, B0); PG8_MMA(1, 1, At, B1); PG8_BAR; PG8_SCHED;
;             PG8_LDB(B0, 1, 0); PG8_LDB(B1, 1, 1); PG8_SCHED; PG8_LDA(At, 1, 0); PG8_STAGE(PG8_SA(0, 1), a2 + hstepA, voffA);
;             PG8_WAIT_V(8); PG8_WAIT_L(0); PG8_BAR; PG8_MMA(0, 0, At, B0); PG8_MMA(0, 1, At, B1); PG8_BAR; PG8_SCHED;
	v_mfma_f32_16x16x32_bf16 v[92:95], v[120:123], v[178:181], v[92:95]
	v_mfma_f32_16x16x32_bf16 v[88:91], v[136:139], v[178:181], v[88:91]
	v_mfma_f32_16x16x32_bf16 v[84:87], v[120:123], v[186:189], v[84:87]
	v_mfma_f32_16x16x32_bf16 v[80:83], v[136:139], v[186:189], v[80:83]
	v_mfma_f32_16x16x32_bf16 v[76:79], v[120:123], v[194:197], v[76:79]
	v_mfma_f32_16x16x32_bf16 v[72:75], v[136:139], v[194:197], v[72:75]
	v_mfma_f32_16x16x32_bf16 v[68:71], v[120:123], v[202:205], v[68:71]
	v_mfma_f32_16x16x32_bf16 v[64:67], v[136:139], v[202:205], v[64:67]
	v_mfma_f32_16x16x32_bf16 v[92:95], v[124:127], v[182:185], v[92:95]
	v_mfma_f32_16x16x32_bf16 v[88:91], v[140:143], v[182:185], v[88:91]
	v_mfma_f32_16x16x32_bf16 v[84:87], v[124:127], v[190:193], v[84:87]
	v_mfma_f32_16x16x32_bf16 v[80:83], v[140:143], v[190:193], v[80:83]
	v_mfma_f32_16x16x32_bf16 v[76:79], v[124:127], v[198:201], v[76:79]
	v_mfma_f32_16x16x32_bf16 v[72:75], v[140:143], v[198:201], v[72:75]
	v_mfma_f32_16x16x32_bf16 v[68:71], v[124:127], v[206:209], v[68:71]
	v_mfma_f32_16x16x32_bf16 v[64:67], v[140:143], v[206:209], v[64:67]
	s_setprio 0
	s_setprio 1
	v_mfma_f32_16x16x32_bf16 v[28:31], v[144:147], v[178:181], v[28:31]
	v_mfma_f32_16x16x32_bf16 v[24:27], v[170:173], v[178:181], v[24:27]
	v_mfma_f32_16x16x32_bf16 v[20:23], v[144:147], v[186:189], v[20:23]
	v_mfma_f32_16x16x32_bf16 v[16:19], v[170:173], v[186:189], v[16:19]
	v_mfma_f32_16x16x32_bf16 v[12:15], v[144:147], v[194:197], v[12:15]
	v_mfma_f32_16x16x32_bf16 v[8:11], v[170:173], v[194:197], v[8:11]
	v_mfma_f32_16x16x32_bf16 v[4:7], v[144:147], v[202:205], v[4:7]
	v_mfma_f32_16x16x32_bf16 v[0:3], v[170:173], v[202:205], v[0:3]
	v_mfma_f32_16x16x32_bf16 v[28:31], v[148:151], v[182:185], v[28:31]
	v_mfma_f32_16x16x32_bf16 v[24:27], v[174:177], v[182:185], v[24:27]
	v_mfma_f32_16x16x32_bf16 v[20:23], v[148:151], v[190:193], v[20:23]
	v_mfma_f32_16x16x32_bf16 v[16:19], v[174:177], v[190:193], v[16:19]
	v_mfma_f32_16x16x32_bf16 v[12:15], v[148:151], v[198:201], v[12:15]
	v_mfma_f32_16x16x32_bf16 v[8:11], v[174:177], v[198:201], v[8:11]
	v_mfma_f32_16x16x32_bf16 v[4:7], v[148:151], v[206:209], v[4:7]
	v_mfma_f32_16x16x32_bf16 v[0:3], v[174:177], v[206:209], v[0:3]
	s_setprio 0
	s_barrier
	ds_read_b128 v[120:123], v225
	ds_read_b128 v[124:127], v225 offset:1024
	ds_read_b128 v[136:139], v225 offset:2048
	ds_read_b128 v[140:143], v225 offset:3072
	ds_read_b128 v[144:147], v226
	ds_read_b128 v[148:151], v226 offset:1024
	ds_read_b128 v[170:173], v226 offset:2048
	ds_read_b128 v[174:177], v226 offset:3072
	s_add_u32 s30, s30, 0x80000
	s_addc_u32 s31, s31, 0
	s_mov_b32 m0, s37
	v_lshl_add_u64 v[218:219], s[30:31], 0, v[154:155]
	ds_read_b128 v[178:181], v223 offset:32768
	ds_read_b128 v[182:185], v223 offset:33792
	ds_read_b128 v[186:189], v223 offset:34816
	ds_read_b128 v[190:193], v223 offset:35840
	ds_read_b128 v[194:197], v223 offset:36864
	ds_read_b128 v[198:201], v223 offset:37888
	ds_read_b128 v[202:205], v223 offset:38912
	ds_read_b128 v[206:209], v223 offset:39936
	global_load_lds_dwordx4 v[218:219], off
	v_lshl_add_u64 v[218:219], s[30:31], 0, v[158:159]
	s_mov_b32 m0, s38
	s_nop 0
	global_load_lds_dwordx4 v[218:219], off
	s_waitcnt vmcnt(8)
	s_waitcnt lgkmcnt(0)
	s_setprio 1
	s_barrier
	v_mfma_f32_16x16x32_bf16 v[132:135], v[120:123], v[178:181], v[132:135]
	v_mfma_f32_16x16x32_bf16 v[128:131], v[136:139], v[178:181], v[128:131]
	v_mfma_f32_16x16x32_bf16 v[100:103], v[120:123], v[186:189], v[100:103]
	v_mfma_f32_16x16x32_bf16 v[96:99], v[136:139], v[186:189], v[96:99]
	v_mfma_f32_16x16x32_bf16 v[116:119], v[120:123], v[194:197], v[116:119]
	v_mfma_f32_16x16x32_bf16 v[112:115], v[136:139], v[194:197], v[112:115]
	v_mfma_f32_16x16x32_bf16 v[108:111], v[120:123], v[202:205], v[108:111]
	v_mfma_f32_16x16x32_bf16 v[104:107], v[136:139], v[202:205], v[104:107]
	v_mfma_f32_16x16x32_bf16 v[132:135], v[124:127], v[182:185], v[132:135]
	v_mfma_f32_16x16x32_bf16 v[128:131], v[140:143], v[182:185], v[128:131]
	v_mfma_f32_16x16x32_bf16 v[100:103], v[124:127], v[190:193], v[100:103]
	v_mfma_f32_16x16x32_bf16 v[96:99], v[140:143], v[190:193], v[96:99]
	v_mfma_f32_16x16x32_bf16 v[116:119], v[124:127], v[198:201], v[116:119]
	v_mfma_f32_16x16x32_bf16 v[112:115], v[140:143], v[198:201], v[112:115]
	v_mfma_f32_16x16x32_bf16 v[108:111], v[124:127], v[206:209], v[108:111]
	v_mfma_f32_16x16x32_bf16 v[104:107], v[140:143], v[206:209], v[104:107]
	s_setprio 0
	s_setprio 1
	v_mfma_f32_16x16x32_bf16 v[60:63], v[144:147], v[178:181], v[60:63]
	v_mfma_f32_16x16x32_bf16 v[56:59], v[170:173], v[178:181], v[56:59]
	v_mfma_f32_16x16x32_bf16 v[52:55], v[144:147], v[186:189], v[52:55]
	v_mfma_f32_16x16x32_bf16 v[48:51], v[170:173], v[186:189], v[48:51]
	v_mfma_f32_16x16x32_bf16 v[44:47], v[144:147], v[194:197], v[44:47]
	v_mfma_f32_16x16x32_bf16 v[40:43], v[170:173], v[194:197], v[40:43]
	v_mfma_f32_16x16x32_bf16 v[36:39], v[144:147], v[202:205], v[36:39]
	v_mfma_f32_16x16x32_bf16 v[32:35], v[170:173], v[202:205], v[32:35]
	v_mfma_f32_16x16x32_bf16 v[60:63], v[148:151], v[182:185], v[60:63]
	v_mfma_f32_16x16x32_bf16 v[56:59], v[174:177], v[182:185], v[56:59]
	v_mfma_f32_16x16x32_bf16 v[52:55], v[148:151], v[190:193], v[52:55]
	v_mfma_f32_16x16x32_bf16 v[48:51], v[174:177], v[190:193], v[48:51]
	v_mfma_f32_16x16x32_bf16 v[44:47], v[148:151], v[198:201], v[44:47]
	v_mfma_f32_16x16x32_bf16 v[40:43], v[174:177], v[198:201], v[40:43]
	v_mfma_f32_16x16x32_bf16 v[36:39], v[148:151], v[206:209], v[36:39]
	v_mfma_f32_16x16x32_bf16 v[32:35], v[174:177], v[206:209], v[32:35]
	s_setprio 0
	s_barrier
; #define PG8_STAGE(bufoff, gbase, voff) do { _Pragma("unroll") for (int _i = 0; _i < 2; ++_i) \
;         __builtin_amdgcn_global_load_lds((const unsigned*)((const char*)(gbase) + (voff)[_i]), (LAS unsigned*)(lds + (bufoff) + ldsw + _i * 8192), 16, 0, 0); } while (0)
; #define PG8_LDA(dst, b, h) do { _Pragma("unroll") for (int m = 0; m < 4; ++m) _Pragma("unroll") for (int k = 0; k < 2; ++k) dst[m][k] = *(const LAS bf16x8*)(lds + PG8_SA(b, h) + aoff + m * 2048 + k * 1024); } while (0)
; #define PG8_MMA(ai, bj, At, Bt) do { __builtin_amdgcn_s_setprio(1); _Pragma("unroll") for (int m = 0; m < 4; ++m) _Pragma("unroll") for (int n = 0; n < 2; ++n) _Pragma("unroll") for (int k = 0; k < 2; ++k) \
;         acc[ai][bj][m][n] = __builtin_amdgcn_mfma_f32_16x16x32_bf16(Bt[n][k], At[m][k], acc[ai][bj][m][n], 0, 0, 0); __builtin_amdgcn_s_setprio(0); } while (0)
; #define PG8_WAIT_V(n) asm volatile("s_waitcnt vmcnt(" #n ")" ::: "memory")
; #define PG8_WAIT_L(n) asm volatile("s_waitcnt lgkmcnt(" #n ")" ::: "memory")
; #define PG8_BAR __builtin_amdgcn_s_barrier()
; #define PG8_SCHED __builtin_amdgcn_sched_barrier(0)
; template <class Epi, class Sched, bool ALIGN_EPI = false, bool SP2 = false>
; __device__ __forceinline__ void gemm_phase(LAS unsigned char* lds, const Gemm g, const Sched& S, const Epi& E) {
;     ...
;         for (int t = 0; t < nt; t += 2) {
;     ...
;             PG8_LDA(At, 1, 1); PG8_STAGE(PG8_SB(1, 0), b3, voffB); PG8_STAGE(PG8_SB(1, 1), b3 + hstepB, voffB); PG8_STAGE(PG8_SA(1, 0), a3, voffA);
;             PG8_WAIT_V(8); PG8_WAIT_L(0); PG8_BAR; PG8_MMA(1, 0, At, B0); PG8_MMA(1, 1, At, B1); PG8_BAR; PG8_SCHED;
	s_add_i32 s30, s47, s34
	v_lshl_add_u64 v[210:211], v[210:211], 0, s[10:11]
	s_mov_b32 m0, s30
	ds_read_b128 v[178:181], v223 offset:49152
	ds_read_b128 v[182:185], v223 offset:50176
	ds_read_b128 v[186:189], v223 offset:51200
	ds_read_b128 v[190:193], v223 offset:52224
	ds_read_b128 v[194:197], v223 offset:53248
	ds_read_b128 v[198:201], v223 offset:54272
	ds_read_b128 v[202:205], v223 offset:55296
	ds_read_b128 v[206:209], v223 offset:56320
	global_load_lds_dwordx4 v[210:211], off
	s_add_i32 m0, s30, 0x2000
	s_add_u32 s28, s28, 0x80080
	v_lshl_add_u64 v[210:211], v[212:213], 0, s[10:11]
	s_addc_u32 s29, s29, 0
	s_add_i32 s30, s48, s34
	global_load_lds_dwordx4 v[210:211], off
	v_lshl_add_u64 v[210:211], s[28:29], 0, v[156:157]
	s_mov_b32 m0, s30
	s_nop 0
	global_load_lds_dwordx4 v[210:211], off
	v_lshl_add_u64 v[210:211], s[28:29], 0, v[160:161]
	s_add_i32 m0, s30, 0x2000
	s_nop 0
	global_load_lds_dwordx4 v[210:211], off
	v_lshl_add_u64 v[210:211], v[214:215], 0, s[10:11]
	s_mov_b32 m0, s39
	s_nop 0
	global_load_lds_dwordx4 v[210:211], off
	v_lshl_add_u64 v[210:211], v[216:217], 0, s[10:11]
	s_mov_b32 m0, s40
	s_nop 0
	global_load_lds_dwordx4 v[210:211], off
	s_waitcnt vmcnt(8)
	s_waitcnt lgkmcnt(0)
	s_setprio 1
	s_barrier
	v_mfma_f32_16x16x32_bf16 v[92:95], v[120:123], v[178:181], v[92:95]
	v_mfma_f32_16x16x32_bf16 v[88:91], v[136:139], v[178:181], v[88:91]
	v_mfma_f32_16x16x32_bf16 v[84:87], v[120:123], v[186:189], v[84:87]
	v_mfma_f32_16x16x32_bf16 v[80:83], v[136:139], v[186:189], v[80:83]
	v_mfma_f32_16x16x32_bf16 v[76:79], v[120:123], v[194:197], v[76:79]
	v_mfma_f32_16x16x32_bf16 v[72:75], v[136:139], v[194:197], v[72:75]
	v_mfma_f32_16x16x32_bf16 v[68:71], v[120:123], v[202:205], v[68:71]
	v_mfma_f32_16x16x32_bf16 v[64:67], v[136:139], v[202:205], v[64:67]
	v_mfma_f32_16x16x32_bf16 v[92:95], v[124:127], v[182:185], v[92:95]
	v_mfma_f32_16x16x32_bf16 v[88:91], v[140:143], v[182:185], v[88:91]
	v_mfma_f32_16x16x32_bf16 v[84:87], v[124:127], v[190:193], v[84:87]
	v_mfma_f32_16x16x32_bf16 v[80:83], v[140:143], v[190:193], v[80:83]
	v_mfma_f32_16x16x32_bf16 v[76:79], v[124:127], v[198:201], v[76:79]
	v_mfma_f32_16x16x32_bf16 v[72:75], v[140:143], v[198:201], v[72:75]
	v_mfma_f32_16x16x32_bf16 v[68:71], v[124:127], v[206:209], v[68:71]
	v_mfma_f32_16x16x32_bf16 v[64:67], v[140:143], v[206:209], v[64:67]
	s_setprio 0
	s_setprio 1
	v_mfma_f32_16x16x32_bf16 v[28:31], v[144:147], v[178:181], v[28:31]
	v_mfma_f32_16x16x32_bf16 v[24:27], v[170:173], v[178:181], v[24:27]
	v_mfma_f32_16x16x32_bf16 v[20:23], v[144:147], v[186:189], v[20:23]
	v_mfma_f32_16x16x32_bf16 v[16:19], v[170:173], v[186:189], v[16:19]
	v_mfma_f32_16x16x32_bf16 v[12:15], v[144:147], v[194:197], v[12:15]
	v_mfma_f32_16x16x32_bf16 v[8:11], v[170:173], v[194:197], v[8:11]
	v_mfma_f32_16x16x32_bf16 v[4:7], v[144:147], v[202:205], v[4:7]
	v_mfma_f32_16x16x32_bf16 v[0:3], v[170:173], v[202:205], v[0:3]
	v_mfma_f32_16x16x32_bf16 v[28:31], v[148:151], v[182:185], v[28:31]
	v_mfma_f32_16x16x32_bf16 v[24:27], v[174:177], v[182:185], v[24:27]
	v_mfma_f32_16x16x32_bf16 v[20:23], v[148:151], v[190:193], v[20:23]
	v_mfma_f32_16x16x32_bf16 v[16:19], v[174:177], v[190:193], v[16:19]
	v_mfma_f32_16x16x32_bf16 v[12:15], v[148:151], v[198:201], v[12:15]
	v_mfma_f32_16x16x32_bf16 v[8:11], v[174:177], v[198:201], v[8:11]
	v_mfma_f32_16x16x32_bf16 v[4:7], v[148:151], v[206:209], v[4:7]
	v_mfma_f32_16x16x32_bf16 v[0:3], v[174:177], v[206:209], v[0:3]
	s_setprio 0
	s_barrier
	s_add_i32 s50, s50, 2
	s_add_u32 s26, s26, 0x100
	s_addc_u32 s27, s27, 0
	s_add_u32 s33, s33, 0x100
	s_addc_u32 s49, s49, 0
	s_cmp_gt_u32 s50, 29
	s_cbranch_scc0 .LBB0_968
	s_and_b64 vcc, exec, s[12:13]
	s_cbranch_vccz .LBB0_971
	s_barrier

; #define PG8_STAGE(bufoff, gbase, voff) do { _Pragma("unroll") for (int _i = 0; _i < 2; ++_i) \
;         __builtin_amdgcn_global_load_lds((const unsigned*)((const char*)(gbase) + (voff)[_i]), (LAS unsigned*)(lds + (bufoff) + ldsw + _i * 8192), 16, 0, 0); } while (0)
; #define PG8_LDA(dst, b, h) do { _Pragma("unroll") for (int m = 0; m < 4; ++m) _Pragma("unroll") for (int k = 0; k < 2; ++k) dst[m][k] = *(const LAS bf16x8*)(lds + PG8_SA(b, h) + aoff + m * 2048 + k * 1024); } while (0)
; #define PG8_LDB(dst, b, h) do { _Pragma("unroll") for (int n = 0; n < 2; ++n) _Pragma("unroll") for (int k = 0; k < 2; ++k) dst[n][k] = *(const LAS bf16x8*)(lds + PG8_SB(b, h) + boff + n * 2048 + k * 1024); } while (0)
; #define PG8_MMA(ai, bj, At, Bt) do { __builtin_amdgcn_s_setprio(1); _Pragma("unroll") for (int m = 0; m < 4; ++m) _Pragma("unroll") for (int n = 0; n < 2; ++n) _Pragma("unroll") for (int k = 0; k < 2; ++k) \
;         acc[ai][bj][m][n] = __builtin_amdgcn_mfma_f32_16x16x32_bf16(Bt[n][k], At[m][k], acc[ai][bj][m][n], 0, 0, 0); __builtin_amdgcn_s_setprio(0); } while (0)
; #define PG8_WAIT_V(n) asm volatile("s_waitcnt vmcnt(" #n ")" ::: "memory")
; #define PG8_WAIT_L(n) asm volatile("s_waitcnt lgkmcnt(" #n ")" ::: "memory")
; #define PG8_BAR __builtin_amdgcn_s_barrier()
; template <class Epi, class Sched, bool ALIGN_EPI = false, bool SP2 = false>
; __device__ __forceinline__ void gemm_phase(LAS unsigned char* lds, const Gemm g, const Sched& S, const Epi& E) {
;     ...
;             const bool last = (t == nt - 2);
;             const char* a1 = cA + (size_t)(t + 1) * kstep;
;             const char* a2 = last ? nA : cA + (size_t)(t + 2) * kstep; const char* b2 = last ? nB : cB + (size_t)(t + 2) * kstep;
;             const char* a3 = a2 + kstep; const char* b3 = b2 + kstep;
;             if (last && has_next) S.a_ready(nxt);
;             if constexpr (SP2) {
;             PG8_LDB(B0, 0, 0); PG8_LDB(B1, 0, 1); PG8_SCHED; PG8_LDA(At, 0, 0); PG8_STAGE(PG8_SA(1, 1), a1 + hstepA, voffA);
;             PG8_WAIT_V(8); PG8_WAIT_L(0); PG8_BAR; PG8_MMA(0, 0, At, B0); PG8_MMA(0, 1, At, B1); PG8_BAR; PG8_SCHED;
;             PG8_LDA(At, 0, 1); PG8_STAGE(PG8_SB(0, 0), b2, voffB); PG8_STAGE(PG8_SB(0, 1), b2 + hstepB, voffB); PG8_STAGE(PG8_SA(0, 0), a2, voffA);
;             PG8_WAIT_V(8); PG8_WAIT_L(0); PG8_BAR; PG8_MMA(1, 0, At, B0); PG8_MMA(1, 1, At, B1); PG8_BAR; PG8_SCHED;
.LBB0_1055:
	ds_read_b128 v[80:83], v171
	ds_read_b128 v[88:91], v171 offset:1024
	ds_read_b128 v[92:95], v171 offset:2048
	ds_read_b128 v[96:99], v171 offset:3072
	ds_read_b128 v[162:165], v172
	ds_read_b128 v[166:169], v172 offset:1024
	ds_read_b128 v[178:181], v172 offset:2048
	ds_read_b128 v[182:185], v172 offset:3072
	s_add_u32 s26, s24, 0xfff80080
	s_addc_u32 s27, s25, -1
	s_cmp_eq_u32 s53, 28
	s_cselect_b32 s29, s17, s27
	s_cselect_b32 s28, s49, s26
	s_cselect_b32 s27, s15, s52
	s_cselect_b32 s26, s50, s51
	v_lshl_add_u64 v[218:219], s[24:25], 0, v[154:155]
	s_add_i32 m0, s23, 0xc000
	ds_read_b128 v[186:189], v173
	ds_read_b128 v[190:193], v173 offset:1024
	ds_read_b128 v[194:197], v173 offset:2048
	ds_read_b128 v[198:201], v173 offset:3072
	ds_read_b128 v[202:205], v173 offset:4096
	ds_read_b128 v[206:209], v173 offset:5120
	ds_read_b128 v[210:213], v173 offset:6144
	ds_read_b128 v[214:217], v173 offset:7168
	global_load_lds_dwordx4 v[218:219], off
	v_lshl_add_u64 v[218:219], s[24:25], 0, v[156:157]
	s_add_i32 m0, s23, 0xe000
	s_nop 0
	global_load_lds_dwordx4 v[218:219], off
	s_waitcnt vmcnt(8)
	s_waitcnt lgkmcnt(0)
	s_setprio 1
	s_barrier
	v_mfma_f32_16x16x32_bf16 v[140:143], v[80:83], v[186:189], v[140:143]
	v_mfma_f32_16x16x32_bf16 v[136:139], v[92:95], v[186:189], v[136:139]
	v_mfma_f32_16x16x32_bf16 v[124:127], v[80:83], v[194:197], v[124:127]
	v_mfma_f32_16x16x32_bf16 v[120:123], v[92:95], v[194:197], v[120:123]
	v_mfma_f32_16x16x32_bf16 v[108:111], v[80:83], v[202:205], v[108:111]
	v_mfma_f32_16x16x32_bf16 v[104:107], v[92:95], v[202:205], v[104:107]
	v_mfma_f32_16x16x32_bf16 v[76:79], v[80:83], v[210:213], v[76:79]
	v_mfma_f32_16x16x32_bf16 v[72:75], v[92:95], v[210:213], v[72:75]
	v_mfma_f32_16x16x32_bf16 v[140:143], v[88:91], v[190:193], v[140:143]
	v_mfma_f32_16x16x32_bf16 v[136:139], v[96:99], v[190:193], v[136:139]
	v_mfma_f32_16x16x32_bf16 v[124:127], v[88:91], v[198:201], v[124:127]
	v_mfma_f32_16x16x32_bf16 v[120:123], v[96:99], v[198:201], v[120:123]
	v_mfma_f32_16x16x32_bf16 v[108:111], v[88:91], v[206:209], v[108:111]
	v_mfma_f32_16x16x32_bf16 v[104:107], v[96:99], v[206:209], v[104:107]
	v_mfma_f32_16x16x32_bf16 v[76:79], v[88:91], v[214:217], v[76:79]
	v_mfma_f32_16x16x32_bf16 v[72:75], v[96:99], v[214:217], v[72:75]
	s_setprio 0
	s_setprio 1
	v_mfma_f32_16x16x32_bf16 v[132:135], v[162:165], v[186:189], v[132:135]
	v_mfma_f32_16x16x32_bf16 v[128:131], v[178:181], v[186:189], v[128:131]
	v_mfma_f32_16x16x32_bf16 v[116:119], v[162:165], v[194:197], v[116:119]
	v_mfma_f32_16x16x32_bf16 v[112:115], v[178:181], v[194:197], v[112:115]
	v_mfma_f32_16x16x32_bf16 v[100:103], v[162:165], v[202:205], v[100:103]
	v_mfma_f32_16x16x32_bf16 v[84:87], v[178:181], v[202:205], v[84:87]
	v_mfma_f32_16x16x32_bf16 v[68:71], v[162:165], v[210:213], v[68:71]
	v_mfma_f32_16x16x32_bf16 v[64:67], v[178:181], v[210:213], v[64:67]
	v_mfma_f32_16x16x32_bf16 v[132:135], v[166:169], v[190:193], v[132:135]
	v_mfma_f32_16x16x32_bf16 v[128:131], v[182:185], v[190:193], v[128:131]
	v_mfma_f32_16x16x32_bf16 v[116:119], v[166:169], v[198:201], v[116:119]
	v_mfma_f32_16x16x32_bf16 v[112:115], v[182:185], v[198:201], v[112:115]
	v_mfma_f32_16x16x32_bf16 v[100:103], v[166:169], v[206:209], v[100:103]
	v_mfma_f32_16x16x32_bf16 v[84:87], v[182:185], v[206:209], v[84:87]
	v_mfma_f32_16x16x32_bf16 v[68:71], v[166:169], v[214:217], v[68:71]
	v_mfma_f32_16x16x32_bf16 v[64:67], v[182:185], v[214:217], v[64:67]
	s_setprio 0
	s_barrier
	s_add_i32 s54, s43, s30
	v_lshl_add_u64 v[218:219], s[26:27], 0, v[146:147]
	s_mov_b32 m0, s54
	ds_read_b128 v[186:189], v173 offset:16384
	ds_read_b128 v[190:193], v173 offset:17408
	ds_read_b128 v[194:197], v173 offset:18432
	ds_read_b128 v[198:201], v173 offset:19456
	ds_read_b128 v[202:205], v173 offset:20480
	ds_read_b128 v[206:209], v173 offset:21504
	ds_read_b128 v[210:213], v173 offset:22528
	ds_read_b128 v[214:217], v173 offset:23552
	global_load_lds_dwordx4 v[218:219], off
	s_add_i32 m0, s54, 0x2000
	s_add_u32 s54, s26, 0x80000
	v_lshl_add_u64 v[220:221], s[26:27], 0, v[150:151]
	s_addc_u32 s55, s27, 0
	s_add_i32 s56, s44, s30
	global_load_lds_dwordx4 v[220:221], off
	v_lshl_add_u64 v[222:223], s[54:55], 0, v[146:147]
	s_mov_b32 m0, s56
	v_lshl_add_u64 v[224:225], s[28:29], 0, v[148:149]
	global_load_lds_dwordx4 v[222:223], off
	v_lshl_add_u64 v[222:223], s[54:55], 0, v[150:151]
	s_add_i32 m0, s56, 0x2000
	s_nop 0
	global_load_lds_dwordx4 v[222:223], off
	v_lshl_add_u64 v[222:223], s[28:29], 0, v[144:145]
	s_mov_b32 m0, s23
	s_nop 0
	global_load_lds_dwordx4 v[222:223], off
	s_mov_b32 m0, s35
	s_nop 0
	global_load_lds_dwordx4 v[224:225], off
	s_waitcnt vmcnt(8)
	s_waitcnt lgkmcnt(0)
	s_setprio 1
	s_barrier
; #define PG8_STAGE(bufoff, gbase, voff) do { _Pragma("unroll") for (int _i = 0; _i < 2; ++_i) \
;         __builtin_amdgcn_global_load_lds((const unsigned*)((const char*)(gbase) + (voff)[_i]), (LAS unsigned*)(lds + (bufoff) + ldsw + _i * 8192), 16, 0, 0); } while (0)
; #define PG8_LDA(dst, b, h) do { _Pragma("unroll") for (int m = 0; m < 4; ++m) _Pragma("unroll") for (int k = 0; k < 2; ++k) dst[m][k] = *(const LAS bf16x8*)(lds + PG8_SA(b, h) + aoff + m * 2048 + k * 1024); } while (0)
; #define PG8_LDB(dst, b, h) do { _Pragma("unroll") for (int n = 0; n < 2; ++n) _Pragma("unroll") for (int k = 0; k < 2; ++k) dst[n][k] = *(const LAS bf16x8*)(lds + PG8_SB(b, h) + boff + n * 2048 + k * 1024); } while (0)
; #define PG8_MMA(ai, bj, At, Bt) do { __builtin_amdgcn_s_setprio(1); _Pragma("unroll") for (int m = 0; m < 4; ++m) _Pragma("unroll") for (int n = 0; n < 2; ++n) _Pragma("unroll") for (int k = 0; k < 2; ++k) \
;         acc[ai][bj][m][n] = __builtin_amdgcn_mfma_f32_16x16x32_bf16(Bt[n][k], At[m][k], acc[ai][bj][m][n], 0, 0, 0); __builtin_amdgcn_s_setprio(0); } while (0)
; #define PG8_WAIT_V(n) asm volatile("s_waitcnt vmcnt(" #n ")" ::: "memory")
; #define PG8_WAIT_L(n) asm volatile("s_waitcnt lgkmcnt(" #n ")" ::: "memory")
; #define PG8_BAR __builtin_amdgcn_s_barrier()
; #define PG8_SCHED __builtin_amdgcn_sched_barrier(0)
; template <class Epi, class Sched, bool ALIGN_EPI = false, bool SP2 = false>
; __device__ __forceinline__ void gemm_phase(LAS unsigned char* lds, const Gemm g, const Sched& S, const Epi& E) {
;     ...
;             PG8_WAIT_V(8); PG8_WAIT_L(0); PG8_BAR; PG8_MMA(1, 0, At, B0); PG8_MMA(1, 1, At, B1); PG8_BAR; PG8_SCHED;
;             PG8_LDB(B0, 1, 0); PG8_LDB(B1, 1, 1); PG8_SCHED; PG8_LDA(At, 1, 0); PG8_STAGE(PG8_SA(0, 1), a2 + hstepA, voffA);
;             PG8_WAIT_V(8); PG8_WAIT_L(0); PG8_BAR; PG8_MMA(0, 0, At, B0); PG8_MMA(0, 1, At, B1); PG8_BAR; PG8_SCHED;
	v_mfma_f32_16x16x32_bf16 v[60:63], v[80:83], v[186:189], v[60:63]
	v_mfma_f32_16x16x32_bf16 v[56:59], v[92:95], v[186:189], v[56:59]
	v_mfma_f32_16x16x32_bf16 v[44:47], v[80:83], v[194:197], v[44:47]
	v_mfma_f32_16x16x32_bf16 v[40:43], v[92:95], v[194:197], v[40:43]
	v_mfma_f32_16x16x32_bf16 v[28:31], v[80:83], v[202:205], v[28:31]
	v_mfma_f32_16x16x32_bf16 v[24:27], v[92:95], v[202:205], v[24:27]
	v_mfma_f32_16x16x32_bf16 v[12:15], v[80:83], v[210:213], v[12:15]
	v_mfma_f32_16x16x32_bf16 v[8:11], v[92:95], v[210:213], v[8:11]
	v_mfma_f32_16x16x32_bf16 v[60:63], v[88:91], v[190:193], v[60:63]
	v_mfma_f32_16x16x32_bf16 v[56:59], v[96:99], v[190:193], v[56:59]
	v_mfma_f32_16x16x32_bf16 v[44:47], v[88:91], v[198:201], v[44:47]
	v_mfma_f32_16x16x32_bf16 v[40:43], v[96:99], v[198:201], v[40:43]
	v_mfma_f32_16x16x32_bf16 v[28:31], v[88:91], v[206:209], v[28:31]
	v_mfma_f32_16x16x32_bf16 v[24:27], v[96:99], v[206:209], v[24:27]
	v_mfma_f32_16x16x32_bf16 v[12:15], v[88:91], v[214:217], v[12:15]
	v_mfma_f32_16x16x32_bf16 v[8:11], v[96:99], v[214:217], v[8:11]
	s_setprio 0
	s_setprio 1
	v_mfma_f32_16x16x32_bf16 v[52:55], v[162:165], v[186:189], v[52:55]
	v_mfma_f32_16x16x32_bf16 v[48:51], v[178:181], v[186:189], v[48:51]
	v_mfma_f32_16x16x32_bf16 v[36:39], v[162:165], v[194:197], v[36:39]
	v_mfma_f32_16x16x32_bf16 v[32:35], v[178:181], v[194:197], v[32:35]
	v_mfma_f32_16x16x32_bf16 v[20:23], v[162:165], v[202:205], v[20:23]
	v_mfma_f32_16x16x32_bf16 v[16:19], v[178:181], v[202:205], v[16:19]
	v_mfma_f32_16x16x32_bf16 v[4:7], v[162:165], v[210:213], v[4:7]
	v_mfma_f32_16x16x32_bf16 v[0:3], v[178:181], v[210:213], v[0:3]
	v_mfma_f32_16x16x32_bf16 v[52:55], v[166:169], v[190:193], v[52:55]
	v_mfma_f32_16x16x32_bf16 v[48:51], v[182:185], v[190:193], v[48:51]
	v_mfma_f32_16x16x32_bf16 v[36:39], v[166:169], v[198:201], v[36:39]
	v_mfma_f32_16x16x32_bf16 v[32:35], v[182:185], v[198:201], v[32:35]
	v_mfma_f32_16x16x32_bf16 v[20:23], v[166:169], v[206:209], v[20:23]
	v_mfma_f32_16x16x32_bf16 v[16:19], v[182:185], v[206:209], v[16:19]
	v_mfma_f32_16x16x32_bf16 v[4:7], v[166:169], v[214:217], v[4:7]
	v_mfma_f32_16x16x32_bf16 v[0:3], v[182:185], v[214:217], v[0:3]
	s_setprio 0
	s_barrier
	ds_read_b128 v[80:83], v175
	ds_read_b128 v[88:91], v175 offset:1024
	ds_read_b128 v[92:95], v175 offset:2048
	ds_read_b128 v[96:99], v175 offset:3072
	ds_read_b128 v[162:165], v176
	ds_read_b128 v[166:169], v176 offset:1024
	ds_read_b128 v[178:181], v176 offset:2048
	ds_read_b128 v[182:185], v176 offset:3072
	s_add_u32 s28, s28, 0x80000
	s_addc_u32 s29, s29, 0
	s_mov_b32 m0, s36
	v_lshl_add_u64 v[226:227], s[28:29], 0, v[144:145]
	ds_read_b128 v[186:189], v173 offset:32768
	ds_read_b128 v[190:193], v173 offset:33792
	ds_read_b128 v[194:197], v173 offset:34816
	ds_read_b128 v[198:201], v173 offset:35840
	ds_read_b128 v[202:205], v173 offset:36864
	ds_read_b128 v[206:209], v173 offset:37888
	ds_read_b128 v[210:213], v173 offset:38912
	ds_read_b128 v[214:217], v173 offset:39936
	global_load_lds_dwordx4 v[226:227], off
	v_lshl_add_u64 v[226:227], s[28:29], 0, v[148:149]
	s_mov_b32 m0, s37
	s_nop 0
	global_load_lds_dwordx4 v[226:227], off
	s_waitcnt vmcnt(8)
	s_waitcnt lgkmcnt(0)
	s_setprio 1
	s_barrier
	v_mfma_f32_16x16x32_bf16 v[140:143], v[80:83], v[186:189], v[140:143]
	v_mfma_f32_16x16x32_bf16 v[136:139], v[92:95], v[186:189], v[136:139]
	v_mfma_f32_16x16x32_bf16 v[124:127], v[80:83], v[194:197], v[124:127]
	v_mfma_f32_16x16x32_bf16 v[120:123], v[92:95], v[194:197], v[120:123]
	v_mfma_f32_16x16x32_bf16 v[108:111], v[80:83], v[202:205], v[108:111]
	v_mfma_f32_16x16x32_bf16 v[104:107], v[92:95], v[202:205], v[104:107]
	v_mfma_f32_16x16x32_bf16 v[76:79], v[80:83], v[210:213], v[76:79]
	v_mfma_f32_16x16x32_bf16 v[72:75], v[92:95], v[210:213], v[72:75]
	v_mfma_f32_16x16x32_bf16 v[140:143], v[88:91], v[190:193], v[140:143]
	v_mfma_f32_16x16x32_bf16 v[136:139], v[96:99], v[190:193], v[136:139]
	v_mfma_f32_16x16x32_bf16 v[124:127], v[88:91], v[198:201], v[124:127]
	v_mfma_f32_16x16x32_bf16 v[120:123], v[96:99], v[198:201], v[120:123]
	v_mfma_f32_16x16x32_bf16 v[108:111], v[88:91], v[206:209], v[108:111]
	v_mfma_f32_16x16x32_bf16 v[104:107], v[96:99], v[206:209], v[104:107]
	v_mfma_f32_16x16x32_bf16 v[76:79], v[88:91], v[214:217], v[76:79]
	v_mfma_f32_16x16x32_bf16 v[72:75], v[96:99], v[214:217], v[72:75]
	s_setprio 0
	s_setprio 1
	v_mfma_f32_16x16x32_bf16 v[132:135], v[162:165], v[186:189], v[132:135]
	v_mfma_f32_16x16x32_bf16 v[128:131], v[178:181], v[186:189], v[128:131]
	v_mfma_f32_16x16x32_bf16 v[116:119], v[162:165], v[194:197], v[116:119]
	v_mfma_f32_16x16x32_bf16 v[112:115], v[178:181], v[194:197], v[112:115]
	v_mfma_f32_16x16x32_bf16 v[100:103], v[162:165], v[202:205], v[100:103]
	v_mfma_f32_16x16x32_bf16 v[84:87], v[178:181], v[202:205], v[84:87]
	v_mfma_f32_16x16x32_bf16 v[68:71], v[162:165], v[210:213], v[68:71]
	v_mfma_f32_16x16x32_bf16 v[64:67], v[178:181], v[210:213], v[64:67]
	v_mfma_f32_16x16x32_bf16 v[132:135], v[166:169], v[190:193], v[132:135]
	v_mfma_f32_16x16x32_bf16 v[128:131], v[182:185], v[190:193], v[128:131]
	v_mfma_f32_16x16x32_bf16 v[116:119], v[166:169], v[198:201], v[116:119]
	v_mfma_f32_16x16x32_bf16 v[112:115], v[182:185], v[198:201], v[112:115]
	v_mfma_f32_16x16x32_bf16 v[100:103], v[166:169], v[206:209], v[100:103]
	v_mfma_f32_16x16x32_bf16 v[84:87], v[182:185], v[206:209], v[84:87]
	v_mfma_f32_16x16x32_bf16 v[68:71], v[166:169], v[214:217], v[68:71]
	v_mfma_f32_16x16x32_bf16 v[64:67], v[182:185], v[214:217], v[64:67]
	s_setprio 0
	s_barrier
; #define PG8_STAGE(bufoff, gbase, voff) do { _Pragma("unroll") for (int _i = 0; _i < 2; ++_i) \
;         __builtin_amdgcn_global_load_lds((const unsigned*)((const char*)(gbase) + (voff)[_i]), (LAS unsigned*)(lds + (bufoff) + ldsw + _i * 8192), 16, 0, 0); } while (0)
; #define PG8_LDA(dst, b, h) do { _Pragma("unroll") for (int m = 0; m < 4; ++m) _Pragma("unroll") for (int k = 0; k < 2; ++k) dst[m][k] = *(const LAS bf16x8*)(lds + PG8_SA(b, h) + aoff + m * 2048 + k * 1024); } while (0)
; #define PG8_MMA(ai, bj, At, Bt) do { __builtin_amdgcn_s_setprio(1); _Pragma("unroll") for (int m = 0; m < 4; ++m) _Pragma("unroll") for (int n = 0; n < 2; ++n) _Pragma("unroll") for (int k = 0; k < 2; ++k) \
;         acc[ai][bj][m][n] = __builtin_amdgcn_mfma_f32_16x16x32_bf16(Bt[n][k], At[m][k], acc[ai][bj][m][n], 0, 0, 0); __builtin_amdgcn_s_setprio(0); } while (0)
; #define PG8_WAIT_V(n) asm volatile("s_waitcnt vmcnt(" #n ")" ::: "memory")
; #define PG8_WAIT_L(n) asm volatile("s_waitcnt lgkmcnt(" #n ")" ::: "memory")
; #define PG8_BAR __builtin_amdgcn_s_barrier()
; #define PG8_SCHED __builtin_amdgcn_sched_barrier(0)
; template <class Epi, class Sched, bool ALIGN_EPI = false, bool SP2 = false>
; __device__ __forceinline__ void gemm_phase(LAS unsigned char* lds, const Gemm g, const Sched& S, const Epi& E) {
;     ...
;         for (int t = 0; t < nt; t += 2) {
;     ...
;             PG8_LDA(At, 1, 1); PG8_STAGE(PG8_SB(1, 0), b3, voffB); PG8_STAGE(PG8_SB(1, 1), b3 + hstepB, voffB); PG8_STAGE(PG8_SA(1, 0), a3, voffA);
;             PG8_WAIT_V(8); PG8_WAIT_L(0); PG8_BAR; PG8_MMA(1, 0, At, B0); PG8_MMA(1, 1, At, B1); PG8_BAR; PG8_SCHED;
	s_add_i32 s28, s47, s30
	v_lshl_add_u64 v[218:219], v[218:219], 0, s[8:9]
	s_mov_b32 m0, s28
	ds_read_b128 v[186:189], v173 offset:49152
	ds_read_b128 v[190:193], v173 offset:50176
	ds_read_b128 v[194:197], v173 offset:51200
	ds_read_b128 v[198:201], v173 offset:52224
	ds_read_b128 v[202:205], v173 offset:53248
	ds_read_b128 v[206:209], v173 offset:54272
	ds_read_b128 v[210:213], v173 offset:55296
	ds_read_b128 v[214:217], v173 offset:56320
	global_load_lds_dwordx4 v[218:219], off
	s_add_i32 m0, s28, 0x2000
	s_add_u32 s26, s26, 0x80080
	v_lshl_add_u64 v[218:219], v[220:221], 0, s[8:9]
	s_addc_u32 s27, s27, 0
	s_add_i32 s28, s48, s30
	global_load_lds_dwordx4 v[218:219], off
	v_lshl_add_u64 v[218:219], s[26:27], 0, v[146:147]
	s_mov_b32 m0, s28
	s_nop 0
	global_load_lds_dwordx4 v[218:219], off
	v_lshl_add_u64 v[218:219], s[26:27], 0, v[150:151]
	s_add_i32 m0, s28, 0x2000
	s_nop 0
	global_load_lds_dwordx4 v[218:219], off
	v_lshl_add_u64 v[218:219], v[222:223], 0, s[8:9]
	s_mov_b32 m0, s40
	s_nop 0
	global_load_lds_dwordx4 v[218:219], off
	v_lshl_add_u64 v[218:219], v[224:225], 0, s[8:9]
	s_mov_b32 m0, s41
	s_nop 0
	global_load_lds_dwordx4 v[218:219], off
	s_waitcnt vmcnt(8)
	s_waitcnt lgkmcnt(0)
	s_setprio 1
	s_barrier
	v_mfma_f32_16x16x32_bf16 v[60:63], v[80:83], v[186:189], v[60:63]
	v_mfma_f32_16x16x32_bf16 v[56:59], v[92:95], v[186:189], v[56:59]
	v_mfma_f32_16x16x32_bf16 v[44:47], v[80:83], v[194:197], v[44:47]
	v_mfma_f32_16x16x32_bf16 v[40:43], v[92:95], v[194:197], v[40:43]
	v_mfma_f32_16x16x32_bf16 v[28:31], v[80:83], v[202:205], v[28:31]
	v_mfma_f32_16x16x32_bf16 v[24:27], v[92:95], v[202:205], v[24:27]
	v_mfma_f32_16x16x32_bf16 v[12:15], v[80:83], v[210:213], v[12:15]
	v_mfma_f32_16x16x32_bf16 v[8:11], v[92:95], v[210:213], v[8:11]
	v_mfma_f32_16x16x32_bf16 v[60:63], v[88:91], v[190:193], v[60:63]
	v_mfma_f32_16x16x32_bf16 v[56:59], v[96:99], v[190:193], v[56:59]
	v_mfma_f32_16x16x32_bf16 v[44:47], v[88:91], v[198:201], v[44:47]
	v_mfma_f32_16x16x32_bf16 v[40:43], v[96:99], v[198:201], v[40:43]
	v_mfma_f32_16x16x32_bf16 v[28:31], v[88:91], v[206:209], v[28:31]
	v_mfma_f32_16x16x32_bf16 v[24:27], v[96:99], v[206:209], v[24:27]
	v_mfma_f32_16x16x32_bf16 v[12:15], v[88:91], v[214:217], v[12:15]
	v_mfma_f32_16x16x32_bf16 v[8:11], v[96:99], v[214:217], v[8:11]
	s_setprio 0
	s_setprio 1
	v_mfma_f32_16x16x32_bf16 v[52:55], v[162:165], v[186:189], v[52:55]
	v_mfma_f32_16x16x32_bf16 v[48:51], v[178:181], v[186:189], v[48:51]
	v_mfma_f32_16x16x32_bf16 v[36:39], v[162:165], v[194:197], v[36:39]
	v_mfma_f32_16x16x32_bf16 v[32:35], v[178:181], v[194:197], v[32:35]
	v_mfma_f32_16x16x32_bf16 v[20:23], v[162:165], v[202:205], v[20:23]
	v_mfma_f32_16x16x32_bf16 v[16:19], v[178:181], v[202:205], v[16:19]
	v_mfma_f32_16x16x32_bf16 v[4:7], v[162:165], v[210:213], v[4:7]
	v_mfma_f32_16x16x32_bf16 v[0:3], v[178:181], v[210:213], v[0:3]
	v_mfma_f32_16x16x32_bf16 v[52:55], v[166:169], v[190:193], v[52:55]
	v_mfma_f32_16x16x32_bf16 v[48:51], v[182:185], v[190:193], v[48:51]
	v_mfma_f32_16x16x32_bf16 v[36:39], v[166:169], v[198:201], v[36:39]
	v_mfma_f32_16x16x32_bf16 v[32:35], v[182:185], v[198:201], v[32:35]
	v_mfma_f32_16x16x32_bf16 v[20:23], v[166:169], v[206:209], v[20:23]
	v_mfma_f32_16x16x32_bf16 v[16:19], v[182:185], v[206:209], v[16:19]
	v_mfma_f32_16x16x32_bf16 v[4:7], v[166:169], v[214:217], v[4:7]
	v_mfma_f32_16x16x32_bf16 v[0:3], v[182:185], v[214:217], v[0:3]
	s_setprio 0
	s_barrier
	s_add_i32 s53, s53, 2
	s_add_u32 s24, s24, 0x100
	s_addc_u32 s25, s25, 0
	s_add_u32 s51, s51, 0x100
	s_addc_u32 s52, s52, 0
	s_cmp_gt_u32 s53, 29
	s_cbranch_scc0 .LBB0_1055
	s_and_b64 vcc, exec, s[10:11]
	s_cbranch_vccz .LBB0_1058
	s_barrier

; #define PG8_STAGE(bufoff, gbase, voff) do { _Pragma("unroll") for (int _i = 0; _i < 2; ++_i) \
;         __builtin_amdgcn_global_load_lds((const unsigned*)((const char*)(gbase) + (voff)[_i]), (LAS unsigned*)(lds + (bufoff) + ldsw + _i * 8192), 16, 0, 0); } while (0)
; #define PG8_LDA(dst, b, h) do { _Pragma("unroll") for (int m = 0; m < 4; ++m) _Pragma("unroll") for (int k = 0; k < 2; ++k) dst[m][k] = *(const LAS bf16x8*)(lds + PG8_SA(b, h) + aoff + m * 2048 + k * 1024); } while (0)
; #define PG8_LDB(dst, b, h) do { _Pragma("unroll") for (int n = 0; n < 2; ++n) _Pragma("unroll") for (int k = 0; k < 2; ++k) dst[n][k] = *(const LAS bf16x8*)(lds + PG8_SB(b, h) + boff + n * 2048 + k * 1024); } while (0)
; #define PG8_MMA(ai, bj, At, Bt) do { __builtin_amdgcn_s_setprio(1); _Pragma("unroll") for (int m = 0; m < 4; ++m) _Pragma("unroll") for (int n = 0; n < 2; ++n) _Pragma("unroll") for (int k = 0; k < 2; ++k) \
;         acc[ai][bj][m][n] = __builtin_amdgcn_mfma_f32_16x16x32_bf16(Bt[n][k], At[m][k], acc[ai][bj][m][n], 0, 0, 0); __builtin_amdgcn_s_setprio(0); } while (0)
; #define PG8_WAIT_V(n) asm volatile("s_waitcnt vmcnt(" #n ")" ::: "memory")
; #define PG8_WAIT_L(n) asm volatile("s_waitcnt lgkmcnt(" #n ")" ::: "memory")
; #define PG8_BAR __builtin_amdgcn_s_barrier()
; template <class Epi, class Sched, bool ALIGN_EPI = false, bool SP2 = false>
; __device__ __forceinline__ void gemm_phase(LAS unsigned char* lds, const Gemm g, const Sched& S, const Epi& E) {
;     ...
;             const bool last = (t == nt - 2);
;             const char* a1 = cA + (size_t)(t + 1) * kstep;
;             const char* a2 = last ? nA : cA + (size_t)(t + 2) * kstep; const char* b2 = last ? nB : cB + (size_t)(t + 2) * kstep;
;             const char* a3 = a2 + kstep; const char* b3 = b2 + kstep;
;             if (last && has_next) S.a_ready(nxt);
;             if constexpr (SP2) {
;             PG8_LDB(B0, 0, 0); PG8_LDB(B1, 0, 1); PG8_SCHED; PG8_LDA(At, 0, 0); PG8_STAGE(PG8_SA(1, 1), a1 + hstepA, voffA);
;             PG8_WAIT_V(8); PG8_WAIT_L(0); PG8_BAR; PG8_MMA(0, 0, At, B0); PG8_MMA(0, 1, At, B1); PG8_BAR; PG8_SCHED;
;             PG8_LDA(At, 0, 1); PG8_STAGE(PG8_SB(0, 0), b2, voffB); PG8_STAGE(PG8_SB(0, 1), b2 + hstepB, voffB); PG8_STAGE(PG8_SA(0, 0), a2, voffA);
;             PG8_WAIT_V(8); PG8_WAIT_L(0); PG8_BAR; PG8_MMA(1, 0, At, B0); PG8_MMA(1, 1, At, B1); PG8_BAR; PG8_SCHED;
.LBB0_1138:
	ds_read_b128 v[128:131], v176
	ds_read_b128 v[132:135], v176 offset:1024
	ds_read_b128 v[152:155], v176 offset:2048
	ds_read_b128 v[156:159], v176 offset:3072
	ds_read_b128 v[160:163], v177
	ds_read_b128 v[164:167], v177 offset:1024
	ds_read_b128 v[168:171], v177 offset:2048
	ds_read_b128 v[182:185], v177 offset:3072
	s_add_u32 s22, s20, 0xffea0080
	s_addc_u32 s23, s21, -1
	s_cmpk_eq_i32 s49, 0x54
	s_cselect_b32 s25, s3, s23
	s_cselect_b32 s24, s2, s22
	s_cselect_b32 s23, s19, s48
	s_cselect_b32 s22, s18, s47
	v_lshl_add_u64 v[172:173], s[20:21], 0, v[144:145]
	s_add_i32 m0, s28, 0xc000
	ds_read_b128 v[186:189], v178
	ds_read_b128 v[190:193], v178 offset:1024
	ds_read_b128 v[194:197], v178 offset:2048
	ds_read_b128 v[198:201], v178 offset:3072
	ds_read_b128 v[202:205], v178 offset:4096
	ds_read_b128 v[206:209], v178 offset:5120
	ds_read_b128 v[210:213], v178 offset:6144
	ds_read_b128 v[214:217], v178 offset:7168
	global_load_lds_dwordx4 v[172:173], off
	v_lshl_add_u64 v[172:173], s[20:21], 0, v[146:147]
	s_add_i32 m0, s28, 0xe000
	s_nop 0
	global_load_lds_dwordx4 v[172:173], off
	s_waitcnt vmcnt(8)
	s_waitcnt lgkmcnt(0)
	s_setprio 1
	s_barrier
	v_mfma_f32_16x16x32_bf16 v[124:127], v[128:131], v[186:189], v[124:127]
	v_mfma_f32_16x16x32_bf16 v[120:123], v[152:155], v[186:189], v[120:123]
	v_mfma_f32_16x16x32_bf16 v[116:119], v[128:131], v[194:197], v[116:119]
	v_mfma_f32_16x16x32_bf16 v[112:115], v[152:155], v[194:197], v[112:115]
	v_mfma_f32_16x16x32_bf16 v[108:111], v[128:131], v[202:205], v[108:111]
	v_mfma_f32_16x16x32_bf16 v[104:107], v[152:155], v[202:205], v[104:107]
	v_mfma_f32_16x16x32_bf16 v[100:103], v[128:131], v[210:213], v[100:103]
	v_mfma_f32_16x16x32_bf16 v[96:99], v[152:155], v[210:213], v[96:99]
	v_mfma_f32_16x16x32_bf16 v[124:127], v[132:135], v[190:193], v[124:127]
	v_mfma_f32_16x16x32_bf16 v[120:123], v[156:159], v[190:193], v[120:123]
	v_mfma_f32_16x16x32_bf16 v[116:119], v[132:135], v[198:201], v[116:119]
	v_mfma_f32_16x16x32_bf16 v[112:115], v[156:159], v[198:201], v[112:115]
	v_mfma_f32_16x16x32_bf16 v[108:111], v[132:135], v[206:209], v[108:111]
	v_mfma_f32_16x16x32_bf16 v[104:107], v[156:159], v[206:209], v[104:107]
	v_mfma_f32_16x16x32_bf16 v[100:103], v[132:135], v[214:217], v[100:103]
	v_mfma_f32_16x16x32_bf16 v[96:99], v[156:159], v[214:217], v[96:99]
	s_setprio 0
	s_setprio 1
	v_mfma_f32_16x16x32_bf16 v[68:71], v[160:163], v[186:189], v[68:71]
	v_mfma_f32_16x16x32_bf16 v[60:63], v[168:171], v[186:189], v[60:63]
	v_mfma_f32_16x16x32_bf16 v[52:55], v[160:163], v[194:197], v[52:55]
	v_mfma_f32_16x16x32_bf16 v[48:51], v[168:171], v[194:197], v[48:51]
	v_mfma_f32_16x16x32_bf16 v[44:47], v[160:163], v[202:205], v[44:47]
	v_mfma_f32_16x16x32_bf16 v[40:43], v[168:171], v[202:205], v[40:43]
	v_mfma_f32_16x16x32_bf16 v[36:39], v[160:163], v[210:213], v[36:39]
	v_mfma_f32_16x16x32_bf16 v[32:35], v[168:171], v[210:213], v[32:35]
	v_mfma_f32_16x16x32_bf16 v[68:71], v[164:167], v[190:193], v[68:71]
	v_mfma_f32_16x16x32_bf16 v[60:63], v[182:185], v[190:193], v[60:63]
	v_mfma_f32_16x16x32_bf16 v[52:55], v[164:167], v[198:201], v[52:55]
	v_mfma_f32_16x16x32_bf16 v[48:51], v[182:185], v[198:201], v[48:51]
	v_mfma_f32_16x16x32_bf16 v[44:47], v[164:167], v[206:209], v[44:47]
	v_mfma_f32_16x16x32_bf16 v[40:43], v[182:185], v[206:209], v[40:43]
	v_mfma_f32_16x16x32_bf16 v[36:39], v[164:167], v[214:217], v[36:39]
	v_mfma_f32_16x16x32_bf16 v[32:35], v[182:185], v[214:217], v[32:35]
	s_setprio 0
	s_barrier
	s_add_i32 s50, s40, s27
	v_lshl_add_u64 v[172:173], s[22:23], 0, v[138:139]
	s_mov_b32 m0, s50
	ds_read_b128 v[186:189], v178 offset:16384
	ds_read_b128 v[190:193], v178 offset:17408
	ds_read_b128 v[194:197], v178 offset:18432
	ds_read_b128 v[198:201], v178 offset:19456
	ds_read_b128 v[202:205], v178 offset:20480
	ds_read_b128 v[206:209], v178 offset:21504
	ds_read_b128 v[210:213], v178 offset:22528
	ds_read_b128 v[214:217], v178 offset:23552
	global_load_lds_dwordx4 v[172:173], off
	s_add_i32 m0, s50, 0x2000
	s_add_u32 s50, s22, 0x160000
	v_lshl_add_u64 v[218:219], s[22:23], 0, v[142:143]
	s_addc_u32 s51, s23, 0
	s_add_i32 s52, s41, s27
	global_load_lds_dwordx4 v[218:219], off
	v_lshl_add_u64 v[220:221], s[50:51], 0, v[138:139]
	s_mov_b32 m0, s52
	v_lshl_add_u64 v[222:223], s[24:25], 0, v[140:141]
	global_load_lds_dwordx4 v[220:221], off
	v_lshl_add_u64 v[220:221], s[50:51], 0, v[142:143]
	s_add_i32 m0, s52, 0x2000
	s_nop 0
	global_load_lds_dwordx4 v[220:221], off
	v_lshl_add_u64 v[220:221], s[24:25], 0, v[136:137]
	s_mov_b32 m0, s28
	s_nop 0
	global_load_lds_dwordx4 v[220:221], off
	s_mov_b32 m0, s29
	s_nop 0
	global_load_lds_dwordx4 v[222:223], off
	s_waitcnt vmcnt(8)
	s_waitcnt lgkmcnt(0)
	s_setprio 1
	s_barrier
; #define PG8_STAGE(bufoff, gbase, voff) do { _Pragma("unroll") for (int _i = 0; _i < 2; ++_i) \
;         __builtin_amdgcn_global_load_lds((const unsigned*)((const char*)(gbase) + (voff)[_i]), (LAS unsigned*)(lds + (bufoff) + ldsw + _i * 8192), 16, 0, 0); } while (0)
; #define PG8_LDA(dst, b, h) do { _Pragma("unroll") for (int m = 0; m < 4; ++m) _Pragma("unroll") for (int k = 0; k < 2; ++k) dst[m][k] = *(const LAS bf16x8*)(lds + PG8_SA(b, h) + aoff + m * 2048 + k * 1024); } while (0)
; #define PG8_LDB(dst, b, h) do { _Pragma("unroll") for (int n = 0; n < 2; ++n) _Pragma("unroll") for (int k = 0; k < 2; ++k) dst[n][k] = *(const LAS bf16x8*)(lds + PG8_SB(b, h) + boff + n * 2048 + k * 1024); } while (0)
; #define PG8_MMA(ai, bj, At, Bt) do { __builtin_amdgcn_s_setprio(1); _Pragma("unroll") for (int m = 0; m < 4; ++m) _Pragma("unroll") for (int n = 0; n < 2; ++n) _Pragma("unroll") for (int k = 0; k < 2; ++k) \
;         acc[ai][bj][m][n] = __builtin_amdgcn_mfma_f32_16x16x32_bf16(Bt[n][k], At[m][k], acc[ai][bj][m][n], 0, 0, 0); __builtin_amdgcn_s_setprio(0); } while (0)
; #define PG8_WAIT_V(n) asm volatile("s_waitcnt vmcnt(" #n ")" ::: "memory")
; #define PG8_WAIT_L(n) asm volatile("s_waitcnt lgkmcnt(" #n ")" ::: "memory")
; #define PG8_BAR __builtin_amdgcn_s_barrier()
; #define PG8_SCHED __builtin_amdgcn_sched_barrier(0)
; template <class Epi, class Sched, bool ALIGN_EPI = false, bool SP2 = false>
; __device__ __forceinline__ void gemm_phase(LAS unsigned char* lds, const Gemm g, const Sched& S, const Epi& E) {
;     ...
;             PG8_WAIT_V(8); PG8_WAIT_L(0); PG8_BAR; PG8_MMA(1, 0, At, B0); PG8_MMA(1, 1, At, B1); PG8_BAR; PG8_SCHED;
;             PG8_LDB(B0, 1, 0); PG8_LDB(B1, 1, 1); PG8_SCHED; PG8_LDA(At, 1, 0); PG8_STAGE(PG8_SA(0, 1), a2 + hstepA, voffA);
;             PG8_WAIT_V(8); PG8_WAIT_L(0); PG8_BAR; PG8_MMA(0, 0, At, B0); PG8_MMA(0, 1, At, B1); PG8_BAR; PG8_SCHED;
	v_mfma_f32_16x16x32_bf16 v[92:95], v[128:131], v[186:189], v[92:95]
	v_mfma_f32_16x16x32_bf16 v[88:91], v[152:155], v[186:189], v[88:91]
	v_mfma_f32_16x16x32_bf16 v[84:87], v[128:131], v[194:197], v[84:87]
	v_mfma_f32_16x16x32_bf16 v[80:83], v[152:155], v[194:197], v[80:83]
	v_mfma_f32_16x16x32_bf16 v[76:79], v[128:131], v[202:205], v[76:79]
	v_mfma_f32_16x16x32_bf16 v[72:75], v[152:155], v[202:205], v[72:75]
	v_mfma_f32_16x16x32_bf16 v[64:67], v[128:131], v[210:213], v[64:67]
	v_mfma_f32_16x16x32_bf16 v[56:59], v[152:155], v[210:213], v[56:59]
	v_mfma_f32_16x16x32_bf16 v[92:95], v[132:135], v[190:193], v[92:95]
	v_mfma_f32_16x16x32_bf16 v[88:91], v[156:159], v[190:193], v[88:91]
	v_mfma_f32_16x16x32_bf16 v[84:87], v[132:135], v[198:201], v[84:87]
	v_mfma_f32_16x16x32_bf16 v[80:83], v[156:159], v[198:201], v[80:83]
	v_mfma_f32_16x16x32_bf16 v[76:79], v[132:135], v[206:209], v[76:79]
	v_mfma_f32_16x16x32_bf16 v[72:75], v[156:159], v[206:209], v[72:75]
	v_mfma_f32_16x16x32_bf16 v[64:67], v[132:135], v[214:217], v[64:67]
	v_mfma_f32_16x16x32_bf16 v[56:59], v[156:159], v[214:217], v[56:59]
	s_setprio 0
	s_setprio 1
	v_mfma_f32_16x16x32_bf16 v[28:31], v[160:163], v[186:189], v[28:31]
	v_mfma_f32_16x16x32_bf16 v[24:27], v[168:171], v[186:189], v[24:27]
	v_mfma_f32_16x16x32_bf16 v[20:23], v[160:163], v[194:197], v[20:23]
	v_mfma_f32_16x16x32_bf16 v[16:19], v[168:171], v[194:197], v[16:19]
	v_mfma_f32_16x16x32_bf16 v[12:15], v[160:163], v[202:205], v[12:15]
	v_mfma_f32_16x16x32_bf16 v[8:11], v[168:171], v[202:205], v[8:11]
	v_mfma_f32_16x16x32_bf16 v[4:7], v[160:163], v[210:213], v[4:7]
	v_mfma_f32_16x16x32_bf16 v[0:3], v[168:171], v[210:213], v[0:3]
	v_mfma_f32_16x16x32_bf16 v[28:31], v[164:167], v[190:193], v[28:31]
	v_mfma_f32_16x16x32_bf16 v[24:27], v[182:185], v[190:193], v[24:27]
	v_mfma_f32_16x16x32_bf16 v[20:23], v[164:167], v[198:201], v[20:23]
	v_mfma_f32_16x16x32_bf16 v[16:19], v[182:185], v[198:201], v[16:19]
	v_mfma_f32_16x16x32_bf16 v[12:15], v[164:167], v[206:209], v[12:15]
	v_mfma_f32_16x16x32_bf16 v[8:11], v[182:185], v[206:209], v[8:11]
	v_mfma_f32_16x16x32_bf16 v[4:7], v[164:167], v[214:217], v[4:7]
	v_mfma_f32_16x16x32_bf16 v[0:3], v[182:185], v[214:217], v[0:3]
	s_setprio 0
	s_barrier
	ds_read_b128 v[128:131], v179
	ds_read_b128 v[132:135], v179 offset:1024
	ds_read_b128 v[152:155], v179 offset:2048
	ds_read_b128 v[156:159], v179 offset:3072
	ds_read_b128 v[160:163], v180
	ds_read_b128 v[164:167], v180 offset:1024
	ds_read_b128 v[168:171], v180 offset:2048
	ds_read_b128 v[182:185], v180 offset:3072
	s_add_u32 s24, s24, 0x160000
	s_addc_u32 s25, s25, 0
	s_mov_b32 m0, s30
	v_lshl_add_u64 v[224:225], s[24:25], 0, v[136:137]
	ds_read_b128 v[186:189], v178 offset:32768
	ds_read_b128 v[190:193], v178 offset:33792
	ds_read_b128 v[194:197], v178 offset:34816
	ds_read_b128 v[198:201], v178 offset:35840
	ds_read_b128 v[202:205], v178 offset:36864
	ds_read_b128 v[206:209], v178 offset:37888
	ds_read_b128 v[210:213], v178 offset:38912
	ds_read_b128 v[214:217], v178 offset:39936
	global_load_lds_dwordx4 v[224:225], off
	v_lshl_add_u64 v[224:225], s[24:25], 0, v[140:141]
	s_mov_b32 m0, s31
	s_nop 0
	global_load_lds_dwordx4 v[224:225], off
	s_waitcnt vmcnt(8)
	s_waitcnt lgkmcnt(0)
	s_setprio 1
	s_barrier
	v_mfma_f32_16x16x32_bf16 v[124:127], v[128:131], v[186:189], v[124:127]
	v_mfma_f32_16x16x32_bf16 v[120:123], v[152:155], v[186:189], v[120:123]
	v_mfma_f32_16x16x32_bf16 v[116:119], v[128:131], v[194:197], v[116:119]
	v_mfma_f32_16x16x32_bf16 v[112:115], v[152:155], v[194:197], v[112:115]
	v_mfma_f32_16x16x32_bf16 v[108:111], v[128:131], v[202:205], v[108:111]
	v_mfma_f32_16x16x32_bf16 v[104:107], v[152:155], v[202:205], v[104:107]
	v_mfma_f32_16x16x32_bf16 v[100:103], v[128:131], v[210:213], v[100:103]
	v_mfma_f32_16x16x32_bf16 v[96:99], v[152:155], v[210:213], v[96:99]
	v_mfma_f32_16x16x32_bf16 v[124:127], v[132:135], v[190:193], v[124:127]
	v_mfma_f32_16x16x32_bf16 v[120:123], v[156:159], v[190:193], v[120:123]
	v_mfma_f32_16x16x32_bf16 v[116:119], v[132:135], v[198:201], v[116:119]
	v_mfma_f32_16x16x32_bf16 v[112:115], v[156:159], v[198:201], v[112:115]
	v_mfma_f32_16x16x32_bf16 v[108:111], v[132:135], v[206:209], v[108:111]
	v_mfma_f32_16x16x32_bf16 v[104:107], v[156:159], v[206:209], v[104:107]
	v_mfma_f32_16x16x32_bf16 v[100:103], v[132:135], v[214:217], v[100:103]
	v_mfma_f32_16x16x32_bf16 v[96:99], v[156:159], v[214:217], v[96:99]
	s_setprio 0
	s_setprio 1
	v_mfma_f32_16x16x32_bf16 v[68:71], v[160:163], v[186:189], v[68:71]
	v_mfma_f32_16x16x32_bf16 v[60:63], v[168:171], v[186:189], v[60:63]
	v_mfma_f32_16x16x32_bf16 v[52:55], v[160:163], v[194:197], v[52:55]
	v_mfma_f32_16x16x32_bf16 v[48:51], v[168:171], v[194:197], v[48:51]
	v_mfma_f32_16x16x32_bf16 v[44:47], v[160:163], v[202:205], v[44:47]
	v_mfma_f32_16x16x32_bf16 v[40:43], v[168:171], v[202:205], v[40:43]
	v_mfma_f32_16x16x32_bf16 v[36:39], v[160:163], v[210:213], v[36:39]
	v_mfma_f32_16x16x32_bf16 v[32:35], v[168:171], v[210:213], v[32:35]
	v_mfma_f32_16x16x32_bf16 v[68:71], v[164:167], v[190:193], v[68:71]
	v_mfma_f32_16x16x32_bf16 v[60:63], v[182:185], v[190:193], v[60:63]
	v_mfma_f32_16x16x32_bf16 v[52:55], v[164:167], v[198:201], v[52:55]
	v_mfma_f32_16x16x32_bf16 v[48:51], v[182:185], v[198:201], v[48:51]
	v_mfma_f32_16x16x32_bf16 v[44:47], v[164:167], v[206:209], v[44:47]
	v_mfma_f32_16x16x32_bf16 v[40:43], v[182:185], v[206:209], v[40:43]
	v_mfma_f32_16x16x32_bf16 v[36:39], v[164:167], v[214:217], v[36:39]
	v_mfma_f32_16x16x32_bf16 v[32:35], v[182:185], v[214:217], v[32:35]
	s_setprio 0
	s_barrier
; #define PG8_STAGE(bufoff, gbase, voff) do { _Pragma("unroll") for (int _i = 0; _i < 2; ++_i) \
;         __builtin_amdgcn_global_load_lds((const unsigned*)((const char*)(gbase) + (voff)[_i]), (LAS unsigned*)(lds + (bufoff) + ldsw + _i * 8192), 16, 0, 0); } while (0)
; #define PG8_LDA(dst, b, h) do { _Pragma("unroll") for (int m = 0; m < 4; ++m) _Pragma("unroll") for (int k = 0; k < 2; ++k) dst[m][k] = *(const LAS bf16x8*)(lds + PG8_SA(b, h) + aoff + m * 2048 + k * 1024); } while (0)
; #define PG8_MMA(ai, bj, At, Bt) do { __builtin_amdgcn_s_setprio(1); _Pragma("unroll") for (int m = 0; m < 4; ++m) _Pragma("unroll") for (int n = 0; n < 2; ++n) _Pragma("unroll") for (int k = 0; k < 2; ++k) \
;         acc[ai][bj][m][n] = __builtin_amdgcn_mfma_f32_16x16x32_bf16(Bt[n][k], At[m][k], acc[ai][bj][m][n], 0, 0, 0); __builtin_amdgcn_s_setprio(0); } while (0)
; #define PG8_WAIT_V(n) asm volatile("s_waitcnt vmcnt(" #n ")" ::: "memory")
; #define PG8_WAIT_L(n) asm volatile("s_waitcnt lgkmcnt(" #n ")" ::: "memory")
; #define PG8_BAR __builtin_amdgcn_s_barrier()
; #define PG8_SCHED __builtin_amdgcn_sched_barrier(0)
; template <class Epi, class Sched, bool ALIGN_EPI = false, bool SP2 = false>
; __device__ __forceinline__ void gemm_phase(LAS unsigned char* lds, const Gemm g, const Sched& S, const Epi& E) {
;     ...
;             PG8_LDA(At, 1, 1); PG8_STAGE(PG8_SB(1, 0), b3, voffB); PG8_STAGE(PG8_SB(1, 1), b3 + hstepB, voffB); PG8_STAGE(PG8_SA(1, 0), a3, voffA);
;             PG8_WAIT_V(8); PG8_WAIT_L(0); PG8_BAR; PG8_MMA(1, 0, At, B0); PG8_MMA(1, 1, At, B1); PG8_BAR; PG8_SCHED;
;     ...
;         if constexpr (ALIGN_EPI) { if (wr == 0) PG8_BAR; }
	s_add_i32 s24, s42, s27
	v_lshl_add_u64 v[172:173], v[172:173], 0, s[8:9]
	s_mov_b32 m0, s24
	ds_read_b128 v[186:189], v178 offset:49152
	ds_read_b128 v[190:193], v178 offset:50176
	ds_read_b128 v[194:197], v178 offset:51200
	ds_read_b128 v[198:201], v178 offset:52224
	ds_read_b128 v[202:205], v178 offset:53248
	ds_read_b128 v[206:209], v178 offset:54272
	ds_read_b128 v[210:213], v178 offset:55296
	ds_read_b128 v[214:217], v178 offset:56320
	global_load_lds_dwordx4 v[172:173], off
	s_add_i32 m0, s24, 0x2000
	s_add_u32 s22, s22, 0x160080
	v_lshl_add_u64 v[172:173], v[218:219], 0, s[8:9]
	s_addc_u32 s23, s23, 0
	s_add_i32 s24, s43, s27
	global_load_lds_dwordx4 v[172:173], off
	v_lshl_add_u64 v[172:173], s[22:23], 0, v[138:139]
	s_mov_b32 m0, s24
	s_nop 0
	global_load_lds_dwordx4 v[172:173], off
	v_lshl_add_u64 v[172:173], s[22:23], 0, v[142:143]
	s_add_i32 m0, s24, 0x2000
	s_nop 0
	global_load_lds_dwordx4 v[172:173], off
	v_lshl_add_u64 v[172:173], v[220:221], 0, s[8:9]
	s_mov_b32 m0, s36
	s_nop 0
	global_load_lds_dwordx4 v[172:173], off
	v_lshl_add_u64 v[172:173], v[222:223], 0, s[8:9]
	s_mov_b32 m0, s37
	s_nop 0
	global_load_lds_dwordx4 v[172:173], off
	s_waitcnt vmcnt(8)
	s_waitcnt lgkmcnt(0)
	s_setprio 1
	s_barrier
	v_mfma_f32_16x16x32_bf16 v[92:95], v[128:131], v[186:189], v[92:95]
	v_mfma_f32_16x16x32_bf16 v[88:91], v[152:155], v[186:189], v[88:91]
	v_mfma_f32_16x16x32_bf16 v[84:87], v[128:131], v[194:197], v[84:87]
	v_mfma_f32_16x16x32_bf16 v[80:83], v[152:155], v[194:197], v[80:83]
	v_mfma_f32_16x16x32_bf16 v[76:79], v[128:131], v[202:205], v[76:79]
	v_mfma_f32_16x16x32_bf16 v[72:75], v[152:155], v[202:205], v[72:75]
	v_mfma_f32_16x16x32_bf16 v[64:67], v[128:131], v[210:213], v[64:67]
	v_mfma_f32_16x16x32_bf16 v[56:59], v[152:155], v[210:213], v[56:59]
	v_mfma_f32_16x16x32_bf16 v[92:95], v[132:135], v[190:193], v[92:95]
	v_mfma_f32_16x16x32_bf16 v[88:91], v[156:159], v[190:193], v[88:91]
	v_mfma_f32_16x16x32_bf16 v[84:87], v[132:135], v[198:201], v[84:87]
	v_mfma_f32_16x16x32_bf16 v[80:83], v[156:159], v[198:201], v[80:83]
	v_mfma_f32_16x16x32_bf16 v[76:79], v[132:135], v[206:209], v[76:79]
	v_mfma_f32_16x16x32_bf16 v[72:75], v[156:159], v[206:209], v[72:75]
	v_mfma_f32_16x16x32_bf16 v[64:67], v[132:135], v[214:217], v[64:67]
	v_mfma_f32_16x16x32_bf16 v[56:59], v[156:159], v[214:217], v[56:59]
	s_setprio 0
	s_setprio 1
	v_mfma_f32_16x16x32_bf16 v[28:31], v[160:163], v[186:189], v[28:31]
	v_mfma_f32_16x16x32_bf16 v[24:27], v[168:171], v[186:189], v[24:27]
	v_mfma_f32_16x16x32_bf16 v[20:23], v[160:163], v[194:197], v[20:23]
	v_mfma_f32_16x16x32_bf16 v[16:19], v[168:171], v[194:197], v[16:19]
	v_mfma_f32_16x16x32_bf16 v[12:15], v[160:163], v[202:205], v[12:15]
	v_mfma_f32_16x16x32_bf16 v[8:11], v[168:171], v[202:205], v[8:11]
	v_mfma_f32_16x16x32_bf16 v[4:7], v[160:163], v[210:213], v[4:7]
	v_mfma_f32_16x16x32_bf16 v[0:3], v[168:171], v[210:213], v[0:3]
	v_mfma_f32_16x16x32_bf16 v[28:31], v[164:167], v[190:193], v[28:31]
	v_mfma_f32_16x16x32_bf16 v[24:27], v[182:185], v[190:193], v[24:27]
	v_mfma_f32_16x16x32_bf16 v[20:23], v[164:167], v[198:201], v[20:23]
	v_mfma_f32_16x16x32_bf16 v[16:19], v[182:185], v[198:201], v[16:19]
	v_mfma_f32_16x16x32_bf16 v[12:15], v[164:167], v[206:209], v[12:15]
	v_mfma_f32_16x16x32_bf16 v[8:11], v[182:185], v[206:209], v[8:11]
	v_mfma_f32_16x16x32_bf16 v[4:7], v[164:167], v[214:217], v[4:7]
	v_mfma_f32_16x16x32_bf16 v[0:3], v[182:185], v[214:217], v[0:3]
	s_setprio 0
	s_barrier
	s_add_i32 s49, s49, 2
	s_add_u32 s20, s20, 0x100
	s_addc_u32 s21, s21, 0
	s_add_u32 s47, s47, 0x100
	s_addc_u32 s48, s48, 0
	s_cmpk_gt_u32 s49, 0x55
	s_cbranch_scc0 .LBB0_1138
	s_and_b64 vcc, exec, s[10:11]
	s_cbranch_vccz .LBB0_1141
	s_barrier
